# P6 output tail rewritten: full 128B row segments via per-wave LDS transpose; removed redundant mid-block setprio pairs
# speedup vs baseline: 1.0489x; 1.0100x over previous
.LBB0_245:
	ds_read_b128 v[144:147], v178
	ds_read_b128 v[148:151], v178 offset:1024
	ds_read_b128 v[152:155], v178 offset:2048
	ds_read_b128 v[156:159], v178 offset:3072
	ds_read_b128 v[160:163], v179
	ds_read_b128 v[164:167], v179 offset:1024
	ds_read_b128 v[168:171], v179 offset:2048
	ds_read_b128 v[182:185], v179 offset:3072
	s_add_u32 s46, s44, 0xfffc0080
	s_addc_u32 s47, s45, -1
	s_cmp_eq_u32 s63, 12
	s_cselect_b32 s49, s7, s47
	s_cselect_b32 s48, s37, s46
	s_cselect_b32 s47, s25, s62
	s_cselect_b32 s46, s43, s61
	v_lshl_add_u64 v[206:207], s[44:45], 0, v[136:137]
	s_add_i32 m0, s31, 0xc000
	ds_read_b128 v[186:189], v180
	ds_read_b128 v[190:193], v180 offset:1024
	ds_read_b128 v[194:197], v180 offset:2048
	ds_read_b128 v[198:201], v180 offset:3072
	ds_read_b128 v[202:205], v180 offset:4096
	ds_read_b128 v[210:213], v180 offset:5120
	ds_read_b128 v[214:217], v180 offset:6144
	ds_read_b128 v[218:221], v180 offset:7168
	global_load_lds_dwordx4 v[206:207], off
	v_lshl_add_u64 v[206:207], s[44:45], 0, v[138:139]
	s_add_i32 m0, s31, 0xe000
	s_nop 0
	global_load_lds_dwordx4 v[206:207], off
	s_waitcnt vmcnt(8)
	s_waitcnt lgkmcnt(0)
	s_barrier
	s_setprio 1
	s_waitcnt lgkmcnt(0)
	v_mfma_f32_16x16x32_bf16 v[124:127], v[144:147], v[186:189], v[124:127]
	v_mfma_f32_16x16x32_bf16 v[120:123], v[152:155], v[186:189], v[120:123]
	v_mfma_f32_16x16x32_bf16 v[108:111], v[144:147], v[194:197], v[108:111]
	v_mfma_f32_16x16x32_bf16 v[104:107], v[152:155], v[194:197], v[104:107]
	v_mfma_f32_16x16x32_bf16 v[92:95], v[144:147], v[202:205], v[92:95]
	v_mfma_f32_16x16x32_bf16 v[88:91], v[152:155], v[202:205], v[88:91]
	v_mfma_f32_16x16x32_bf16 v[76:79], v[144:147], v[214:217], v[76:79]
	v_mfma_f32_16x16x32_bf16 v[72:75], v[152:155], v[214:217], v[72:75]
	v_mfma_f32_16x16x32_bf16 v[124:127], v[148:151], v[190:193], v[124:127]
	v_mfma_f32_16x16x32_bf16 v[120:123], v[156:159], v[190:193], v[120:123]
	v_mfma_f32_16x16x32_bf16 v[108:111], v[148:151], v[198:201], v[108:111]
	v_mfma_f32_16x16x32_bf16 v[104:107], v[156:159], v[198:201], v[104:107]
	v_mfma_f32_16x16x32_bf16 v[92:95], v[148:151], v[210:213], v[92:95]
	v_mfma_f32_16x16x32_bf16 v[88:91], v[156:159], v[210:213], v[88:91]
	v_mfma_f32_16x16x32_bf16 v[76:79], v[148:151], v[218:221], v[76:79]
	v_mfma_f32_16x16x32_bf16 v[72:75], v[156:159], v[218:221], v[72:75]
	v_mfma_f32_16x16x32_bf16 v[116:119], v[160:163], v[186:189], v[116:119]
	v_mfma_f32_16x16x32_bf16 v[112:115], v[168:171], v[186:189], v[112:115]
	v_mfma_f32_16x16x32_bf16 v[100:103], v[160:163], v[194:197], v[100:103]
	v_mfma_f32_16x16x32_bf16 v[96:99], v[168:171], v[194:197], v[96:99]
	v_mfma_f32_16x16x32_bf16 v[84:87], v[160:163], v[202:205], v[84:87]
	v_mfma_f32_16x16x32_bf16 v[80:83], v[168:171], v[202:205], v[80:83]
	v_mfma_f32_16x16x32_bf16 v[68:71], v[160:163], v[214:217], v[68:71]
	v_mfma_f32_16x16x32_bf16 v[64:67], v[168:171], v[214:217], v[64:67]
	v_mfma_f32_16x16x32_bf16 v[116:119], v[164:167], v[190:193], v[116:119]
	v_mfma_f32_16x16x32_bf16 v[112:115], v[182:185], v[190:193], v[112:115]
	v_mfma_f32_16x16x32_bf16 v[100:103], v[164:167], v[198:201], v[100:103]
	v_mfma_f32_16x16x32_bf16 v[96:99], v[182:185], v[198:201], v[96:99]
	v_mfma_f32_16x16x32_bf16 v[84:87], v[164:167], v[210:213], v[84:87]
	v_mfma_f32_16x16x32_bf16 v[80:83], v[182:185], v[210:213], v[80:83]
	v_mfma_f32_16x16x32_bf16 v[68:71], v[164:167], v[218:221], v[68:71]
	v_mfma_f32_16x16x32_bf16 v[64:67], v[182:185], v[218:221], v[64:67]
	s_setprio 0
	s_barrier
	s_add_i32 s64, s35, s23
	v_lshl_add_u64 v[206:207], s[46:47], 0, v[130:131]
	s_mov_b32 m0, s64
	ds_read_b128 v[186:189], v180 offset:16384
	ds_read_b128 v[190:193], v180 offset:17408
	ds_read_b128 v[194:197], v180 offset:18432
	ds_read_b128 v[198:201], v180 offset:19456
	ds_read_b128 v[202:205], v180 offset:20480
	ds_read_b128 v[210:213], v180 offset:21504
	ds_read_b128 v[214:217], v180 offset:22528
	ds_read_b128 v[218:221], v180 offset:23552
	global_load_lds_dwordx4 v[206:207], off
	s_add_i32 m0, s64, 0x2000
	s_add_u32 s64, s46, 0x40000
	v_lshl_add_u64 v[222:223], s[46:47], 0, v[134:135]
	s_addc_u32 s65, s47, 0
	s_add_i32 s66, s59, s23
	global_load_lds_dwordx4 v[222:223], off
	v_lshl_add_u64 v[224:225], s[64:65], 0, v[130:131]
	s_mov_b32 m0, s66
	v_lshl_add_u64 v[226:227], s[48:49], 0, v[132:133]
	global_load_lds_dwordx4 v[224:225], off
	v_lshl_add_u64 v[224:225], s[64:65], 0, v[134:135]
	s_add_i32 m0, s66, 0x2000
	s_nop 0
	global_load_lds_dwordx4 v[224:225], off
	v_lshl_add_u64 v[224:225], s[48:49], 0, v[128:129]
	s_mov_b32 m0, s31
	s_nop 0
	global_load_lds_dwordx4 v[224:225], off
	s_mov_b32 m0, s50
	s_nop 0
	global_load_lds_dwordx4 v[226:227], off
	s_waitcnt vmcnt(8)
	s_waitcnt lgkmcnt(0)
	s_barrier
	s_setprio 1
	s_waitcnt lgkmcnt(0)
	v_mfma_f32_16x16x32_bf16 v[60:63], v[144:147], v[186:189], v[60:63]
	v_mfma_f32_16x16x32_bf16 v[56:59], v[152:155], v[186:189], v[56:59]
	v_mfma_f32_16x16x32_bf16 v[44:47], v[144:147], v[194:197], v[44:47]
	v_mfma_f32_16x16x32_bf16 v[40:43], v[152:155], v[194:197], v[40:43]
	v_mfma_f32_16x16x32_bf16 v[28:31], v[144:147], v[202:205], v[28:31]
	v_mfma_f32_16x16x32_bf16 v[24:27], v[152:155], v[202:205], v[24:27]
	v_mfma_f32_16x16x32_bf16 v[12:15], v[144:147], v[214:217], v[12:15]
	v_mfma_f32_16x16x32_bf16 v[8:11], v[152:155], v[214:217], v[8:11]
	v_mfma_f32_16x16x32_bf16 v[60:63], v[148:151], v[190:193], v[60:63]
	v_mfma_f32_16x16x32_bf16 v[56:59], v[156:159], v[190:193], v[56:59]
	v_mfma_f32_16x16x32_bf16 v[44:47], v[148:151], v[198:201], v[44:47]
	v_mfma_f32_16x16x32_bf16 v[40:43], v[156:159], v[198:201], v[40:43]
	v_mfma_f32_16x16x32_bf16 v[28:31], v[148:151], v[210:213], v[28:31]
	v_mfma_f32_16x16x32_bf16 v[24:27], v[156:159], v[210:213], v[24:27]
	v_mfma_f32_16x16x32_bf16 v[12:15], v[148:151], v[218:221], v[12:15]
	v_mfma_f32_16x16x32_bf16 v[8:11], v[156:159], v[218:221], v[8:11]
	v_mfma_f32_16x16x32_bf16 v[52:55], v[160:163], v[186:189], v[52:55]
	v_mfma_f32_16x16x32_bf16 v[48:51], v[168:171], v[186:189], v[48:51]
	v_mfma_f32_16x16x32_bf16 v[36:39], v[160:163], v[194:197], v[36:39]
	v_mfma_f32_16x16x32_bf16 v[32:35], v[168:171], v[194:197], v[32:35]
	v_mfma_f32_16x16x32_bf16 v[20:23], v[160:163], v[202:205], v[20:23]
	v_mfma_f32_16x16x32_bf16 v[16:19], v[168:171], v[202:205], v[16:19]
	v_mfma_f32_16x16x32_bf16 v[4:7], v[160:163], v[214:217], v[4:7]
	v_mfma_f32_16x16x32_bf16 v[0:3], v[168:171], v[214:217], v[0:3]
	v_mfma_f32_16x16x32_bf16 v[52:55], v[164:167], v[190:193], v[52:55]
	v_mfma_f32_16x16x32_bf16 v[48:51], v[182:185], v[190:193], v[48:51]
	v_mfma_f32_16x16x32_bf16 v[36:39], v[164:167], v[198:201], v[36:39]
	v_mfma_f32_16x16x32_bf16 v[32:35], v[182:185], v[198:201], v[32:35]
	v_mfma_f32_16x16x32_bf16 v[20:23], v[164:167], v[210:213], v[20:23]
	v_mfma_f32_16x16x32_bf16 v[16:19], v[182:185], v[210:213], v[16:19]
	v_mfma_f32_16x16x32_bf16 v[4:7], v[164:167], v[218:221], v[4:7]
	v_mfma_f32_16x16x32_bf16 v[0:3], v[182:185], v[218:221], v[0:3]
	s_setprio 0
	s_barrier
	s_add_i32 s64, 0, 0x18000
	s_add_i32 s65, 0, 0x1c000
	v_add_u32_e32 v156, s64, v176
	v_add_u32_e32 v181, s65, v176
	ds_read_b128 v[144:147], v156
	ds_read_b128 v[148:151], v156 offset:1024
	ds_read_b128 v[152:155], v156 offset:2048
	ds_read_b128 v[156:159], v156 offset:3072
	ds_read_b128 v[160:163], v181
	ds_read_b128 v[164:167], v181 offset:1024
	ds_read_b128 v[168:171], v181 offset:2048
	ds_read_b128 v[182:185], v181 offset:3072
	s_add_u32 s48, s48, 0x40000
	s_addc_u32 s49, s49, 0
	s_mov_b32 m0, s51
	v_lshl_add_u64 v[228:229], s[48:49], 0, v[128:129]
	ds_read_b128 v[186:189], v180 offset:32768
	ds_read_b128 v[190:193], v180 offset:33792
	ds_read_b128 v[194:197], v180 offset:34816
	ds_read_b128 v[198:201], v180 offset:35840
	ds_read_b128 v[202:205], v180 offset:36864
	ds_read_b128 v[210:213], v180 offset:37888
	ds_read_b128 v[214:217], v180 offset:38912
	ds_read_b128 v[218:221], v180 offset:39936
	global_load_lds_dwordx4 v[228:229], off
	v_lshl_add_u64 v[228:229], s[48:49], 0, v[132:133]
	s_mov_b32 m0, s52
	s_nop 0
	global_load_lds_dwordx4 v[228:229], off
	s_waitcnt vmcnt(8)
	s_waitcnt lgkmcnt(0)
	s_barrier
	s_setprio 1
	s_waitcnt lgkmcnt(0)
	v_mfma_f32_16x16x32_bf16 v[124:127], v[144:147], v[186:189], v[124:127]
	v_mfma_f32_16x16x32_bf16 v[120:123], v[152:155], v[186:189], v[120:123]
	v_mfma_f32_16x16x32_bf16 v[108:111], v[144:147], v[194:197], v[108:111]
	v_mfma_f32_16x16x32_bf16 v[104:107], v[152:155], v[194:197], v[104:107]
	v_mfma_f32_16x16x32_bf16 v[92:95], v[144:147], v[202:205], v[92:95]
	v_mfma_f32_16x16x32_bf16 v[88:91], v[152:155], v[202:205], v[88:91]
	v_mfma_f32_16x16x32_bf16 v[76:79], v[144:147], v[214:217], v[76:79]
	v_mfma_f32_16x16x32_bf16 v[72:75], v[152:155], v[214:217], v[72:75]
	v_mfma_f32_16x16x32_bf16 v[124:127], v[148:151], v[190:193], v[124:127]
	v_mfma_f32_16x16x32_bf16 v[120:123], v[156:159], v[190:193], v[120:123]
	v_mfma_f32_16x16x32_bf16 v[108:111], v[148:151], v[198:201], v[108:111]
	v_mfma_f32_16x16x32_bf16 v[104:107], v[156:159], v[198:201], v[104:107]
	v_mfma_f32_16x16x32_bf16 v[92:95], v[148:151], v[210:213], v[92:95]
	v_mfma_f32_16x16x32_bf16 v[88:91], v[156:159], v[210:213], v[88:91]
	v_mfma_f32_16x16x32_bf16 v[76:79], v[148:151], v[218:221], v[76:79]
	v_mfma_f32_16x16x32_bf16 v[72:75], v[156:159], v[218:221], v[72:75]
	v_mfma_f32_16x16x32_bf16 v[116:119], v[160:163], v[186:189], v[116:119]
	v_mfma_f32_16x16x32_bf16 v[112:115], v[168:171], v[186:189], v[112:115]
	v_mfma_f32_16x16x32_bf16 v[100:103], v[160:163], v[194:197], v[100:103]
	v_mfma_f32_16x16x32_bf16 v[96:99], v[168:171], v[194:197], v[96:99]
	v_mfma_f32_16x16x32_bf16 v[84:87], v[160:163], v[202:205], v[84:87]
	v_mfma_f32_16x16x32_bf16 v[80:83], v[168:171], v[202:205], v[80:83]
	v_mfma_f32_16x16x32_bf16 v[68:71], v[160:163], v[214:217], v[68:71]
	v_mfma_f32_16x16x32_bf16 v[64:67], v[168:171], v[214:217], v[64:67]
	v_mfma_f32_16x16x32_bf16 v[116:119], v[164:167], v[190:193], v[116:119]
	v_mfma_f32_16x16x32_bf16 v[112:115], v[182:185], v[190:193], v[112:115]
	v_mfma_f32_16x16x32_bf16 v[100:103], v[164:167], v[198:201], v[100:103]
	v_mfma_f32_16x16x32_bf16 v[96:99], v[182:185], v[198:201], v[96:99]
	v_mfma_f32_16x16x32_bf16 v[84:87], v[164:167], v[210:213], v[84:87]
	v_mfma_f32_16x16x32_bf16 v[80:83], v[182:185], v[210:213], v[80:83]
	v_mfma_f32_16x16x32_bf16 v[68:71], v[164:167], v[218:221], v[68:71]
	v_mfma_f32_16x16x32_bf16 v[64:67], v[182:185], v[218:221], v[64:67]
	s_setprio 0
	s_barrier
	s_add_i32 s48, s64, s23
	v_lshl_add_u64 v[206:207], v[206:207], 0, s[16:17]
	s_mov_b32 m0, s48
	ds_read_b128 v[186:189], v180 offset:49152
	ds_read_b128 v[190:193], v180 offset:50176
	ds_read_b128 v[194:197], v180 offset:51200
	ds_read_b128 v[198:201], v180 offset:52224
	ds_read_b128 v[202:205], v180 offset:53248
	ds_read_b128 v[210:213], v180 offset:54272
	ds_read_b128 v[214:217], v180 offset:55296
	ds_read_b128 v[218:221], v180 offset:56320
	global_load_lds_dwordx4 v[206:207], off
	s_add_i32 m0, s48, 0x2000
	s_add_u32 s46, s46, 0x40080
	v_lshl_add_u64 v[206:207], v[222:223], 0, s[16:17]
	s_addc_u32 s47, s47, 0
	s_add_i32 s48, s65, s23
	global_load_lds_dwordx4 v[206:207], off
	v_lshl_add_u64 v[206:207], s[46:47], 0, v[130:131]
	s_mov_b32 m0, s48
	s_nop 0
	global_load_lds_dwordx4 v[206:207], off
	v_lshl_add_u64 v[206:207], s[46:47], 0, v[134:135]
	s_add_i32 m0, s48, 0x2000
	s_nop 0
	global_load_lds_dwordx4 v[206:207], off
	v_lshl_add_u64 v[206:207], v[224:225], 0, s[16:17]
	s_mov_b32 m0, s54
	s_nop 0
	global_load_lds_dwordx4 v[206:207], off
	v_lshl_add_u64 v[206:207], v[226:227], 0, s[16:17]
	s_mov_b32 m0, s55
	s_nop 0
	global_load_lds_dwordx4 v[206:207], off
	s_waitcnt vmcnt(8)
	s_waitcnt lgkmcnt(0)
	s_barrier
	s_setprio 1
	s_waitcnt lgkmcnt(0)
	v_mfma_f32_16x16x32_bf16 v[60:63], v[144:147], v[186:189], v[60:63]
	v_mfma_f32_16x16x32_bf16 v[56:59], v[152:155], v[186:189], v[56:59]
	v_mfma_f32_16x16x32_bf16 v[44:47], v[144:147], v[194:197], v[44:47]
	v_mfma_f32_16x16x32_bf16 v[40:43], v[152:155], v[194:197], v[40:43]
	v_mfma_f32_16x16x32_bf16 v[28:31], v[144:147], v[202:205], v[28:31]
	v_mfma_f32_16x16x32_bf16 v[24:27], v[152:155], v[202:205], v[24:27]
	v_mfma_f32_16x16x32_bf16 v[12:15], v[144:147], v[214:217], v[12:15]
	v_mfma_f32_16x16x32_bf16 v[8:11], v[152:155], v[214:217], v[8:11]
	v_mfma_f32_16x16x32_bf16 v[60:63], v[148:151], v[190:193], v[60:63]
	v_mfma_f32_16x16x32_bf16 v[56:59], v[156:159], v[190:193], v[56:59]
	v_mfma_f32_16x16x32_bf16 v[44:47], v[148:151], v[198:201], v[44:47]
	v_mfma_f32_16x16x32_bf16 v[40:43], v[156:159], v[198:201], v[40:43]
	v_mfma_f32_16x16x32_bf16 v[28:31], v[148:151], v[210:213], v[28:31]
	v_mfma_f32_16x16x32_bf16 v[24:27], v[156:159], v[210:213], v[24:27]
	v_mfma_f32_16x16x32_bf16 v[12:15], v[148:151], v[218:221], v[12:15]
	v_mfma_f32_16x16x32_bf16 v[8:11], v[156:159], v[218:221], v[8:11]
	v_mfma_f32_16x16x32_bf16 v[52:55], v[160:163], v[186:189], v[52:55]
	v_mfma_f32_16x16x32_bf16 v[48:51], v[168:171], v[186:189], v[48:51]
	v_mfma_f32_16x16x32_bf16 v[36:39], v[160:163], v[194:197], v[36:39]
	v_mfma_f32_16x16x32_bf16 v[32:35], v[168:171], v[194:197], v[32:35]
	v_mfma_f32_16x16x32_bf16 v[20:23], v[160:163], v[202:205], v[20:23]
	v_mfma_f32_16x16x32_bf16 v[16:19], v[168:171], v[202:205], v[16:19]
	v_mfma_f32_16x16x32_bf16 v[4:7], v[160:163], v[214:217], v[4:7]
	v_mfma_f32_16x16x32_bf16 v[0:3], v[168:171], v[214:217], v[0:3]
	v_mfma_f32_16x16x32_bf16 v[52:55], v[164:167], v[190:193], v[52:55]
	v_mfma_f32_16x16x32_bf16 v[48:51], v[182:185], v[190:193], v[48:51]
	v_mfma_f32_16x16x32_bf16 v[36:39], v[164:167], v[198:201], v[36:39]
	v_mfma_f32_16x16x32_bf16 v[32:35], v[182:185], v[198:201], v[32:35]
	v_mfma_f32_16x16x32_bf16 v[20:23], v[164:167], v[210:213], v[20:23]
	v_mfma_f32_16x16x32_bf16 v[16:19], v[182:185], v[210:213], v[16:19]
	v_mfma_f32_16x16x32_bf16 v[4:7], v[164:167], v[218:221], v[4:7]
	v_mfma_f32_16x16x32_bf16 v[0:3], v[182:185], v[218:221], v[0:3]
	s_setprio 0
	s_barrier
	s_add_i32 s63, s63, 2
	s_add_u32 s44, s44, 0x100
	s_addc_u32 s45, s45, 0
	s_add_u32 s61, s61, 0x100
	s_addc_u32 s62, s62, 0
	s_cmp_gt_u32 s63, 13
	s_cbranch_scc0 .LBB0_245
	s_and_b64 vcc, exec, s[18:19]
	s_cbranch_vccz .LBB0_248
	s_barrier

.LBB0_307:
	ds_read_b128 v[146:149], v143
	ds_read_b128 v[150:153], v143 offset:1024
	ds_read_b128 v[154:157], v143 offset:2048
	ds_read_b128 v[158:161], v143 offset:3072
	ds_read_b128 v[162:165], v144
	ds_read_b128 v[166:169], v144 offset:1024
	ds_read_b128 v[176:179], v144 offset:2048
	ds_read_b128 v[180:183], v144 offset:3072
	s_add_i32 s71, s46, 2
	s_add_u32 s72, s44, 0x80
	s_addc_u32 s47, s45, 0
	s_cmp_eq_u32 s58, s46
	s_cselect_b32 s46, s40, s72
	s_cselect_b32 s47, s41, s47
	s_cselect_b32 s73, s43, s70
	s_cselect_b32 s72, s42, s69
	v_lshl_add_u64 v[170:171], s[44:45], 0, v[136:137]
	s_add_i32 m0, s49, 0xc000
	ds_read_b128 v[184:187], v145
	ds_read_b128 v[188:191], v145 offset:1024
	ds_read_b128 v[192:195], v145 offset:2048
	ds_read_b128 v[196:199], v145 offset:3072
	ds_read_b128 v[200:203], v145 offset:4096
	ds_read_b128 v[204:207], v145 offset:5120
	ds_read_b128 v[210:213], v145 offset:6144
	ds_read_b128 v[214:217], v145 offset:7168
	global_load_lds_dwordx4 v[170:171], off
	v_lshl_add_u64 v[170:171], s[44:45], 0, v[138:139]
	s_add_i32 m0, s49, 0xe000
	s_nop 0
	global_load_lds_dwordx4 v[170:171], off
	s_waitcnt vmcnt(8)
	s_waitcnt lgkmcnt(0)
	s_barrier
	s_setprio 1
	s_waitcnt lgkmcnt(0)
	v_mfma_f32_16x16x32_bf16 v[120:123], v[146:149], v[184:187], v[120:123]
	v_mfma_f32_16x16x32_bf16 v[124:127], v[154:157], v[184:187], v[124:127]
	v_mfma_f32_16x16x32_bf16 v[108:111], v[146:149], v[192:195], v[108:111]
	v_mfma_f32_16x16x32_bf16 v[104:107], v[154:157], v[192:195], v[104:107]
	v_mfma_f32_16x16x32_bf16 v[92:95], v[146:149], v[200:203], v[92:95]
	v_mfma_f32_16x16x32_bf16 v[88:91], v[154:157], v[200:203], v[88:91]
	v_mfma_f32_16x16x32_bf16 v[76:79], v[146:149], v[210:213], v[76:79]
	v_mfma_f32_16x16x32_bf16 v[72:75], v[154:157], v[210:213], v[72:75]
	v_mfma_f32_16x16x32_bf16 v[120:123], v[150:153], v[188:191], v[120:123]
	v_mfma_f32_16x16x32_bf16 v[124:127], v[158:161], v[188:191], v[124:127]
	v_mfma_f32_16x16x32_bf16 v[108:111], v[150:153], v[196:199], v[108:111]
	v_mfma_f32_16x16x32_bf16 v[104:107], v[158:161], v[196:199], v[104:107]
	v_mfma_f32_16x16x32_bf16 v[92:95], v[150:153], v[204:207], v[92:95]
	v_mfma_f32_16x16x32_bf16 v[88:91], v[158:161], v[204:207], v[88:91]
	v_mfma_f32_16x16x32_bf16 v[76:79], v[150:153], v[214:217], v[76:79]
	v_mfma_f32_16x16x32_bf16 v[72:75], v[158:161], v[214:217], v[72:75]
	v_mfma_f32_16x16x32_bf16 v[116:119], v[162:165], v[184:187], v[116:119]
	v_mfma_f32_16x16x32_bf16 v[112:115], v[176:179], v[184:187], v[112:115]
	v_mfma_f32_16x16x32_bf16 v[100:103], v[162:165], v[192:195], v[100:103]
	v_mfma_f32_16x16x32_bf16 v[96:99], v[176:179], v[192:195], v[96:99]
	v_mfma_f32_16x16x32_bf16 v[84:87], v[162:165], v[200:203], v[84:87]
	v_mfma_f32_16x16x32_bf16 v[80:83], v[176:179], v[200:203], v[80:83]
	v_mfma_f32_16x16x32_bf16 v[68:71], v[162:165], v[210:213], v[68:71]
	v_mfma_f32_16x16x32_bf16 v[64:67], v[176:179], v[210:213], v[64:67]
	v_mfma_f32_16x16x32_bf16 v[116:119], v[166:169], v[188:191], v[116:119]
	v_mfma_f32_16x16x32_bf16 v[112:115], v[180:183], v[188:191], v[112:115]
	v_mfma_f32_16x16x32_bf16 v[100:103], v[166:169], v[196:199], v[100:103]
	v_mfma_f32_16x16x32_bf16 v[96:99], v[180:183], v[196:199], v[96:99]
	v_mfma_f32_16x16x32_bf16 v[84:87], v[166:169], v[204:207], v[84:87]
	v_mfma_f32_16x16x32_bf16 v[80:83], v[180:183], v[204:207], v[80:83]
	v_mfma_f32_16x16x32_bf16 v[68:71], v[166:169], v[214:217], v[68:71]
	v_mfma_f32_16x16x32_bf16 v[64:67], v[180:183], v[214:217], v[64:67]
	s_setprio 0
	s_barrier
	s_add_i32 s74, s60, s48
	v_lshl_add_u64 v[170:171], s[72:73], 0, v[130:131]
	s_mov_b32 m0, s74
	ds_read_b128 v[184:187], v145 offset:16384
	ds_read_b128 v[188:191], v145 offset:17408
	ds_read_b128 v[192:195], v145 offset:18432
	ds_read_b128 v[196:199], v145 offset:19456
	ds_read_b128 v[200:203], v145 offset:20480
	ds_read_b128 v[204:207], v145 offset:21504
	ds_read_b128 v[210:213], v145 offset:22528
	ds_read_b128 v[214:217], v145 offset:23552
	global_load_lds_dwordx4 v[170:171], off
	s_add_i32 m0, s74, 0x2000
	v_lshl_add_u64 v[218:219], s[72:73], 0, v[134:135]
	s_add_u32 s72, s72, s8
	s_addc_u32 s73, s73, s9
	s_add_i32 s74, s61, s48
	global_load_lds_dwordx4 v[218:219], off
	v_lshl_add_u64 v[220:221], s[72:73], 0, v[130:131]
	s_mov_b32 m0, s74
	v_lshl_add_u64 v[222:223], s[72:73], 0, v[134:135]
	global_load_lds_dwordx4 v[220:221], off
	s_add_i32 m0, s74, 0x2000
	v_lshl_add_u64 v[224:225], s[46:47], 0, v[128:129]
	global_load_lds_dwordx4 v[222:223], off
	s_mov_b32 m0, s49
	v_lshl_add_u64 v[226:227], s[46:47], 0, v[132:133]
	global_load_lds_dwordx4 v[224:225], off
	s_mov_b32 m0, s50
	s_nop 0
	global_load_lds_dwordx4 v[226:227], off
	s_waitcnt vmcnt(8)
	s_waitcnt lgkmcnt(0)
	s_barrier
	s_setprio 1
	s_waitcnt lgkmcnt(0)
	v_mfma_f32_16x16x32_bf16 v[60:63], v[146:149], v[184:187], v[60:63]
	v_mfma_f32_16x16x32_bf16 v[56:59], v[154:157], v[184:187], v[56:59]
	v_mfma_f32_16x16x32_bf16 v[44:47], v[146:149], v[192:195], v[44:47]
	v_mfma_f32_16x16x32_bf16 v[40:43], v[154:157], v[192:195], v[40:43]
	v_mfma_f32_16x16x32_bf16 v[28:31], v[146:149], v[200:203], v[28:31]
	v_mfma_f32_16x16x32_bf16 v[24:27], v[154:157], v[200:203], v[24:27]
	v_mfma_f32_16x16x32_bf16 v[12:15], v[146:149], v[210:213], v[12:15]
	v_mfma_f32_16x16x32_bf16 v[8:11], v[154:157], v[210:213], v[8:11]
	v_mfma_f32_16x16x32_bf16 v[60:63], v[150:153], v[188:191], v[60:63]
	v_mfma_f32_16x16x32_bf16 v[56:59], v[158:161], v[188:191], v[56:59]
	v_mfma_f32_16x16x32_bf16 v[44:47], v[150:153], v[196:199], v[44:47]
	v_mfma_f32_16x16x32_bf16 v[40:43], v[158:161], v[196:199], v[40:43]
	v_mfma_f32_16x16x32_bf16 v[28:31], v[150:153], v[204:207], v[28:31]
	v_mfma_f32_16x16x32_bf16 v[24:27], v[158:161], v[204:207], v[24:27]
	v_mfma_f32_16x16x32_bf16 v[12:15], v[150:153], v[214:217], v[12:15]
	v_mfma_f32_16x16x32_bf16 v[8:11], v[158:161], v[214:217], v[8:11]
	v_mfma_f32_16x16x32_bf16 v[52:55], v[162:165], v[184:187], v[52:55]
	v_mfma_f32_16x16x32_bf16 v[48:51], v[176:179], v[184:187], v[48:51]
	v_mfma_f32_16x16x32_bf16 v[36:39], v[162:165], v[192:195], v[36:39]
	v_mfma_f32_16x16x32_bf16 v[32:35], v[176:179], v[192:195], v[32:35]
	v_mfma_f32_16x16x32_bf16 v[20:23], v[162:165], v[200:203], v[20:23]
	v_mfma_f32_16x16x32_bf16 v[16:19], v[176:179], v[200:203], v[16:19]
	v_mfma_f32_16x16x32_bf16 v[4:7], v[162:165], v[210:213], v[4:7]
	v_mfma_f32_16x16x32_bf16 v[0:3], v[176:179], v[210:213], v[0:3]
	v_mfma_f32_16x16x32_bf16 v[52:55], v[166:169], v[188:191], v[52:55]
	v_mfma_f32_16x16x32_bf16 v[48:51], v[180:183], v[188:191], v[48:51]
	v_mfma_f32_16x16x32_bf16 v[36:39], v[166:169], v[196:199], v[36:39]
	v_mfma_f32_16x16x32_bf16 v[32:35], v[180:183], v[196:199], v[32:35]
	v_mfma_f32_16x16x32_bf16 v[20:23], v[166:169], v[204:207], v[20:23]
	v_mfma_f32_16x16x32_bf16 v[16:19], v[180:183], v[204:207], v[16:19]
	v_mfma_f32_16x16x32_bf16 v[4:7], v[166:169], v[214:217], v[4:7]
	v_mfma_f32_16x16x32_bf16 v[0:3], v[180:183], v[214:217], v[0:3]
	s_setprio 0
	s_barrier
	s_add_i32 s72, 0, 0x18000
	s_add_i32 s73, 0, 0x1c000
	v_add_u32_e32 v158, s72, v141
	v_add_u32_e32 v175, s73, v141
	ds_read_b128 v[146:149], v158
	ds_read_b128 v[150:153], v158 offset:1024
	ds_read_b128 v[154:157], v158 offset:2048
	ds_read_b128 v[158:161], v158 offset:3072
	ds_read_b128 v[162:165], v175
	ds_read_b128 v[166:169], v175 offset:1024
	ds_read_b128 v[176:179], v175 offset:2048
	ds_read_b128 v[180:183], v175 offset:3072
	s_add_u32 s46, s46, s8
	s_addc_u32 s47, s47, s9
	s_mov_b32 m0, s51
	v_lshl_add_u64 v[228:229], s[46:47], 0, v[128:129]
	ds_read_b128 v[184:187], v145 offset:32768
	ds_read_b128 v[188:191], v145 offset:33792
	ds_read_b128 v[192:195], v145 offset:34816
	ds_read_b128 v[196:199], v145 offset:35840
	ds_read_b128 v[200:203], v145 offset:36864
	ds_read_b128 v[204:207], v145 offset:37888
	ds_read_b128 v[210:213], v145 offset:38912
	ds_read_b128 v[214:217], v145 offset:39936
	global_load_lds_dwordx4 v[228:229], off
	v_lshl_add_u64 v[228:229], s[46:47], 0, v[132:133]
	s_mov_b32 m0, s52
	s_nop 0
	global_load_lds_dwordx4 v[228:229], off
	s_waitcnt vmcnt(8)
	s_waitcnt lgkmcnt(0)
	s_barrier
	s_setprio 1
	s_waitcnt lgkmcnt(0)
	v_mfma_f32_16x16x32_bf16 v[120:123], v[146:149], v[184:187], v[120:123]
	v_mfma_f32_16x16x32_bf16 v[124:127], v[154:157], v[184:187], v[124:127]
	v_mfma_f32_16x16x32_bf16 v[108:111], v[146:149], v[192:195], v[108:111]
	v_mfma_f32_16x16x32_bf16 v[104:107], v[154:157], v[192:195], v[104:107]
	v_mfma_f32_16x16x32_bf16 v[92:95], v[146:149], v[200:203], v[92:95]
	v_mfma_f32_16x16x32_bf16 v[88:91], v[154:157], v[200:203], v[88:91]
	v_mfma_f32_16x16x32_bf16 v[76:79], v[146:149], v[210:213], v[76:79]
	v_mfma_f32_16x16x32_bf16 v[72:75], v[154:157], v[210:213], v[72:75]
	v_mfma_f32_16x16x32_bf16 v[120:123], v[150:153], v[188:191], v[120:123]
	v_mfma_f32_16x16x32_bf16 v[124:127], v[158:161], v[188:191], v[124:127]
	v_mfma_f32_16x16x32_bf16 v[108:111], v[150:153], v[196:199], v[108:111]
	v_mfma_f32_16x16x32_bf16 v[104:107], v[158:161], v[196:199], v[104:107]
	v_mfma_f32_16x16x32_bf16 v[92:95], v[150:153], v[204:207], v[92:95]
	v_mfma_f32_16x16x32_bf16 v[88:91], v[158:161], v[204:207], v[88:91]
	v_mfma_f32_16x16x32_bf16 v[76:79], v[150:153], v[214:217], v[76:79]
	v_mfma_f32_16x16x32_bf16 v[72:75], v[158:161], v[214:217], v[72:75]
	v_mfma_f32_16x16x32_bf16 v[116:119], v[162:165], v[184:187], v[116:119]
	v_mfma_f32_16x16x32_bf16 v[112:115], v[176:179], v[184:187], v[112:115]
	v_mfma_f32_16x16x32_bf16 v[100:103], v[162:165], v[192:195], v[100:103]
	v_mfma_f32_16x16x32_bf16 v[96:99], v[176:179], v[192:195], v[96:99]
	v_mfma_f32_16x16x32_bf16 v[84:87], v[162:165], v[200:203], v[84:87]
	v_mfma_f32_16x16x32_bf16 v[80:83], v[176:179], v[200:203], v[80:83]
	v_mfma_f32_16x16x32_bf16 v[68:71], v[162:165], v[210:213], v[68:71]
	v_mfma_f32_16x16x32_bf16 v[64:67], v[176:179], v[210:213], v[64:67]
	v_mfma_f32_16x16x32_bf16 v[116:119], v[166:169], v[188:191], v[116:119]
	v_mfma_f32_16x16x32_bf16 v[112:115], v[180:183], v[188:191], v[112:115]
	v_mfma_f32_16x16x32_bf16 v[100:103], v[166:169], v[196:199], v[100:103]
	v_mfma_f32_16x16x32_bf16 v[96:99], v[180:183], v[196:199], v[96:99]
	v_mfma_f32_16x16x32_bf16 v[84:87], v[166:169], v[204:207], v[84:87]
	v_mfma_f32_16x16x32_bf16 v[80:83], v[180:183], v[204:207], v[80:83]
	v_mfma_f32_16x16x32_bf16 v[68:71], v[166:169], v[214:217], v[68:71]
	v_mfma_f32_16x16x32_bf16 v[64:67], v[180:183], v[214:217], v[64:67]
	s_setprio 0
	s_barrier
	s_add_i32 s46, s72, s48
	v_lshl_add_u64 v[170:171], v[170:171], 0, s[16:17]
	s_mov_b32 m0, s46
	ds_read_b128 v[184:187], v145 offset:49152
	ds_read_b128 v[188:191], v145 offset:50176
	ds_read_b128 v[192:195], v145 offset:51200
	ds_read_b128 v[196:199], v145 offset:52224
	ds_read_b128 v[200:203], v145 offset:53248
	ds_read_b128 v[204:207], v145 offset:54272
	ds_read_b128 v[210:213], v145 offset:55296
	ds_read_b128 v[214:217], v145 offset:56320
	global_load_lds_dwordx4 v[170:171], off
	v_lshl_add_u64 v[170:171], v[218:219], 0, s[16:17]
	s_add_i32 m0, s46, 0x2000
	s_add_i32 s46, s73, s48
	global_load_lds_dwordx4 v[170:171], off
	v_lshl_add_u64 v[170:171], v[220:221], 0, s[16:17]
	s_mov_b32 m0, s46
	s_nop 0
	global_load_lds_dwordx4 v[170:171], off
	v_lshl_add_u64 v[170:171], v[222:223], 0, s[16:17]
	s_add_i32 m0, s46, 0x2000
	s_nop 0
	global_load_lds_dwordx4 v[170:171], off
	v_lshl_add_u64 v[170:171], v[224:225], 0, s[16:17]
	s_mov_b32 m0, s54
	s_nop 0
	global_load_lds_dwordx4 v[170:171], off
	v_lshl_add_u64 v[170:171], v[226:227], 0, s[16:17]
	s_mov_b32 m0, s55
	s_nop 0
	global_load_lds_dwordx4 v[170:171], off
	s_waitcnt vmcnt(8)
	s_waitcnt lgkmcnt(0)
	s_barrier
	s_setprio 1
	s_waitcnt lgkmcnt(0)
	v_mfma_f32_16x16x32_bf16 v[60:63], v[146:149], v[184:187], v[60:63]
	v_mfma_f32_16x16x32_bf16 v[56:59], v[154:157], v[184:187], v[56:59]
	v_mfma_f32_16x16x32_bf16 v[44:47], v[146:149], v[192:195], v[44:47]
	v_mfma_f32_16x16x32_bf16 v[40:43], v[154:157], v[192:195], v[40:43]
	v_mfma_f32_16x16x32_bf16 v[28:31], v[146:149], v[200:203], v[28:31]
	v_mfma_f32_16x16x32_bf16 v[24:27], v[154:157], v[200:203], v[24:27]
	v_mfma_f32_16x16x32_bf16 v[12:15], v[146:149], v[210:213], v[12:15]
	v_mfma_f32_16x16x32_bf16 v[8:11], v[154:157], v[210:213], v[8:11]
	v_mfma_f32_16x16x32_bf16 v[60:63], v[150:153], v[188:191], v[60:63]
	v_mfma_f32_16x16x32_bf16 v[56:59], v[158:161], v[188:191], v[56:59]
	v_mfma_f32_16x16x32_bf16 v[44:47], v[150:153], v[196:199], v[44:47]
	v_mfma_f32_16x16x32_bf16 v[40:43], v[158:161], v[196:199], v[40:43]
	v_mfma_f32_16x16x32_bf16 v[28:31], v[150:153], v[204:207], v[28:31]
	v_mfma_f32_16x16x32_bf16 v[24:27], v[158:161], v[204:207], v[24:27]
	v_mfma_f32_16x16x32_bf16 v[12:15], v[150:153], v[214:217], v[12:15]
	v_mfma_f32_16x16x32_bf16 v[8:11], v[158:161], v[214:217], v[8:11]
	v_mfma_f32_16x16x32_bf16 v[52:55], v[162:165], v[184:187], v[52:55]
	v_mfma_f32_16x16x32_bf16 v[48:51], v[176:179], v[184:187], v[48:51]
	v_mfma_f32_16x16x32_bf16 v[36:39], v[162:165], v[192:195], v[36:39]
	v_mfma_f32_16x16x32_bf16 v[32:35], v[176:179], v[192:195], v[32:35]
	v_mfma_f32_16x16x32_bf16 v[20:23], v[162:165], v[200:203], v[20:23]
	v_mfma_f32_16x16x32_bf16 v[16:19], v[176:179], v[200:203], v[16:19]
	v_mfma_f32_16x16x32_bf16 v[4:7], v[162:165], v[210:213], v[4:7]
	v_mfma_f32_16x16x32_bf16 v[0:3], v[176:179], v[210:213], v[0:3]
	v_mfma_f32_16x16x32_bf16 v[52:55], v[166:169], v[188:191], v[52:55]
	v_mfma_f32_16x16x32_bf16 v[48:51], v[180:183], v[188:191], v[48:51]
	v_mfma_f32_16x16x32_bf16 v[36:39], v[166:169], v[196:199], v[36:39]
	v_mfma_f32_16x16x32_bf16 v[32:35], v[180:183], v[196:199], v[32:35]
	v_mfma_f32_16x16x32_bf16 v[20:23], v[166:169], v[204:207], v[20:23]
	v_mfma_f32_16x16x32_bf16 v[16:19], v[180:183], v[204:207], v[16:19]
	v_mfma_f32_16x16x32_bf16 v[4:7], v[166:169], v[214:217], v[4:7]
	v_mfma_f32_16x16x32_bf16 v[0:3], v[180:183], v[214:217], v[0:3]
	s_setprio 0
	s_barrier
	s_add_u32 s44, s44, 0x100
	s_addc_u32 s45, s45, 0
	s_add_u32 s69, s69, 0x100
	s_addc_u32 s70, s70, 0
	s_cmp_ge_i32 s71, s57
	s_mov_b32 s46, s71
	s_cbranch_scc0 .LBB0_307

.LBB0_492:
	ds_read_b128 v[128:131], v179
	ds_read_b128 v[132:135], v179 offset:1024
	ds_read_b128 v[136:139], v179 offset:2048
	ds_read_b128 v[140:143], v179 offset:3072
	ds_read_b128 v[144:147], v187
	ds_read_b128 v[148:151], v187 offset:1024
	ds_read_b128 v[180:183], v187 offset:2048
	ds_read_b128 v[188:191], v187 offset:3072
	s_add_u32 s48, s46, 0xfffc0080
	s_addc_u32 s49, s47, -1
	s_cmp_eq_u32 s66, 12
	s_cselect_b32 s51, s37, s49
	s_cselect_b32 s50, s43, s48
	s_cselect_b32 s49, s25, s65
	s_cselect_b32 s48, s63, s64
	v_lshl_add_u64 v[168:169], s[46:47], 0, v[160:161]
	s_add_i32 m0, s45, 0xc000
	ds_read_b128 v[196:199], v195
	ds_read_b128 v[202:205], v195 offset:1024
	ds_read_b128 v[210:213], v195 offset:2048
	ds_read_b128 v[214:217], v195 offset:3072
	ds_read_b128 v[218:221], v195 offset:4096
	ds_read_b128 v[222:225], v195 offset:5120
	ds_read_b128 v[226:229], v195 offset:6144
	ds_read_b128 v[230:233], v195 offset:7168
	global_load_lds_dwordx4 v[168:169], off
	v_lshl_add_u64 v[168:169], s[46:47], 0, v[162:163]
	s_add_i32 m0, s45, 0xe000
	s_nop 0
	global_load_lds_dwordx4 v[168:169], off
	s_waitcnt vmcnt(8)
	s_waitcnt lgkmcnt(0)
	s_barrier
	s_setprio 1
	s_waitcnt lgkmcnt(0)
	v_mfma_f32_16x16x32_bf16 v[124:127], v[128:131], v[196:199], v[124:127]
	v_mfma_f32_16x16x32_bf16 v[120:123], v[136:139], v[196:199], v[120:123]
	v_mfma_f32_16x16x32_bf16 v[108:111], v[128:131], v[210:213], v[108:111]
	v_mfma_f32_16x16x32_bf16 v[104:107], v[136:139], v[210:213], v[104:107]
	v_mfma_f32_16x16x32_bf16 v[92:95], v[128:131], v[218:221], v[92:95]
	v_mfma_f32_16x16x32_bf16 v[88:91], v[136:139], v[218:221], v[88:91]
	v_mfma_f32_16x16x32_bf16 v[76:79], v[128:131], v[226:229], v[76:79]
	v_mfma_f32_16x16x32_bf16 v[72:75], v[136:139], v[226:229], v[72:75]
	v_mfma_f32_16x16x32_bf16 v[124:127], v[132:135], v[202:205], v[124:127]
	v_mfma_f32_16x16x32_bf16 v[120:123], v[140:143], v[202:205], v[120:123]
	v_mfma_f32_16x16x32_bf16 v[108:111], v[132:135], v[214:217], v[108:111]
	v_mfma_f32_16x16x32_bf16 v[104:107], v[140:143], v[214:217], v[104:107]
	v_mfma_f32_16x16x32_bf16 v[92:95], v[132:135], v[222:225], v[92:95]
	v_mfma_f32_16x16x32_bf16 v[88:91], v[140:143], v[222:225], v[88:91]
	v_mfma_f32_16x16x32_bf16 v[76:79], v[132:135], v[230:233], v[76:79]
	v_mfma_f32_16x16x32_bf16 v[72:75], v[140:143], v[230:233], v[72:75]
	v_mfma_f32_16x16x32_bf16 v[116:119], v[144:147], v[196:199], v[116:119]
	v_mfma_f32_16x16x32_bf16 v[112:115], v[180:183], v[196:199], v[112:115]
	v_mfma_f32_16x16x32_bf16 v[100:103], v[144:147], v[210:213], v[100:103]
	v_mfma_f32_16x16x32_bf16 v[96:99], v[180:183], v[210:213], v[96:99]
	v_mfma_f32_16x16x32_bf16 v[84:87], v[144:147], v[218:221], v[84:87]
	v_mfma_f32_16x16x32_bf16 v[80:83], v[180:183], v[218:221], v[80:83]
	v_mfma_f32_16x16x32_bf16 v[68:71], v[144:147], v[226:229], v[68:71]
	v_mfma_f32_16x16x32_bf16 v[64:67], v[180:183], v[226:229], v[64:67]
	v_mfma_f32_16x16x32_bf16 v[116:119], v[148:151], v[202:205], v[116:119]
	v_mfma_f32_16x16x32_bf16 v[112:115], v[188:191], v[202:205], v[112:115]
	v_mfma_f32_16x16x32_bf16 v[100:103], v[148:151], v[214:217], v[100:103]
	v_mfma_f32_16x16x32_bf16 v[96:99], v[188:191], v[214:217], v[96:99]
	v_mfma_f32_16x16x32_bf16 v[84:87], v[148:151], v[222:225], v[84:87]
	v_mfma_f32_16x16x32_bf16 v[80:83], v[188:191], v[222:225], v[80:83]
	v_mfma_f32_16x16x32_bf16 v[68:71], v[148:151], v[230:233], v[68:71]
	v_mfma_f32_16x16x32_bf16 v[64:67], v[188:191], v[230:233], v[64:67]
	s_setprio 0
	s_barrier
	s_add_i32 s67, s61, s52
	v_lshl_add_u64 v[168:169], s[48:49], 0, v[154:155]
	s_mov_b32 m0, s67
	ds_read_b128 v[196:199], v195 offset:16384
	ds_read_b128 v[202:205], v195 offset:17408
	ds_read_b128 v[210:213], v195 offset:18432
	ds_read_b128 v[214:217], v195 offset:19456
	ds_read_b128 v[218:221], v195 offset:20480
	ds_read_b128 v[222:225], v195 offset:21504
	ds_read_b128 v[226:229], v195 offset:22528
	ds_read_b128 v[230:233], v195 offset:23552
	global_load_lds_dwordx4 v[168:169], off
	s_add_i32 m0, s67, 0x2000
	s_add_u32 s68, s48, 0x40000
	v_lshl_add_u64 v[176:177], s[48:49], 0, v[158:159]
	s_addc_u32 s69, s49, 0
	s_add_i32 s67, s62, s52
	global_load_lds_dwordx4 v[176:177], off
	v_lshl_add_u64 v[184:185], s[68:69], 0, v[154:155]
	s_mov_b32 m0, s67
	v_lshl_add_u64 v[192:193], s[50:51], 0, v[156:157]
	global_load_lds_dwordx4 v[184:185], off
	v_lshl_add_u64 v[184:185], s[68:69], 0, v[158:159]
	s_add_i32 m0, s67, 0x2000
	s_nop 0
	global_load_lds_dwordx4 v[184:185], off
	v_lshl_add_u64 v[184:185], s[50:51], 0, v[152:153]
	s_mov_b32 m0, s45
	s_nop 0
	global_load_lds_dwordx4 v[184:185], off
	s_mov_b32 m0, s53
	s_nop 0
	global_load_lds_dwordx4 v[192:193], off
	s_waitcnt vmcnt(8)
	s_waitcnt lgkmcnt(0)
	s_barrier
	s_setprio 1
	s_waitcnt lgkmcnt(0)
	v_mfma_f32_16x16x32_bf16 v[60:63], v[128:131], v[196:199], v[60:63]
	v_mfma_f32_16x16x32_bf16 v[56:59], v[136:139], v[196:199], v[56:59]
	v_mfma_f32_16x16x32_bf16 v[44:47], v[128:131], v[210:213], v[44:47]
	v_mfma_f32_16x16x32_bf16 v[40:43], v[136:139], v[210:213], v[40:43]
	v_mfma_f32_16x16x32_bf16 v[28:31], v[128:131], v[218:221], v[28:31]
	v_mfma_f32_16x16x32_bf16 v[24:27], v[136:139], v[218:221], v[24:27]
	v_mfma_f32_16x16x32_bf16 v[12:15], v[128:131], v[226:229], v[12:15]
	v_mfma_f32_16x16x32_bf16 v[8:11], v[136:139], v[226:229], v[8:11]
	v_mfma_f32_16x16x32_bf16 v[60:63], v[132:135], v[202:205], v[60:63]
	v_mfma_f32_16x16x32_bf16 v[56:59], v[140:143], v[202:205], v[56:59]
	v_mfma_f32_16x16x32_bf16 v[44:47], v[132:135], v[214:217], v[44:47]
	v_mfma_f32_16x16x32_bf16 v[40:43], v[140:143], v[214:217], v[40:43]
	v_mfma_f32_16x16x32_bf16 v[28:31], v[132:135], v[222:225], v[28:31]
	v_mfma_f32_16x16x32_bf16 v[24:27], v[140:143], v[222:225], v[24:27]
	v_mfma_f32_16x16x32_bf16 v[12:15], v[132:135], v[230:233], v[12:15]
	v_mfma_f32_16x16x32_bf16 v[8:11], v[140:143], v[230:233], v[8:11]
	v_mfma_f32_16x16x32_bf16 v[52:55], v[144:147], v[196:199], v[52:55]
	v_mfma_f32_16x16x32_bf16 v[48:51], v[180:183], v[196:199], v[48:51]
	v_mfma_f32_16x16x32_bf16 v[36:39], v[144:147], v[210:213], v[36:39]
	v_mfma_f32_16x16x32_bf16 v[32:35], v[180:183], v[210:213], v[32:35]
	v_mfma_f32_16x16x32_bf16 v[20:23], v[144:147], v[218:221], v[20:23]
	v_mfma_f32_16x16x32_bf16 v[16:19], v[180:183], v[218:221], v[16:19]
	v_mfma_f32_16x16x32_bf16 v[4:7], v[144:147], v[226:229], v[4:7]
	v_mfma_f32_16x16x32_bf16 v[0:3], v[180:183], v[226:229], v[0:3]
	v_mfma_f32_16x16x32_bf16 v[52:55], v[148:151], v[202:205], v[52:55]
	v_mfma_f32_16x16x32_bf16 v[48:51], v[188:191], v[202:205], v[48:51]
	v_mfma_f32_16x16x32_bf16 v[36:39], v[148:151], v[214:217], v[36:39]
	v_mfma_f32_16x16x32_bf16 v[32:35], v[188:191], v[214:217], v[32:35]
	v_mfma_f32_16x16x32_bf16 v[20:23], v[148:151], v[222:225], v[20:23]
	v_mfma_f32_16x16x32_bf16 v[16:19], v[188:191], v[222:225], v[16:19]
	v_mfma_f32_16x16x32_bf16 v[4:7], v[148:151], v[230:233], v[4:7]
	v_mfma_f32_16x16x32_bf16 v[0:3], v[188:191], v[230:233], v[0:3]
	s_setprio 0
	s_barrier
	s_add_i32 s67, 0, 0x18000
	s_add_i32 s68, 0, 0x1c000
	v_add_u32_e32 v140, s67, v173
	v_add_u32_e32 v170, s68, v173
	ds_read_b128 v[128:131], v140
	ds_read_b128 v[132:135], v140 offset:1024
	ds_read_b128 v[136:139], v140 offset:2048
	ds_read_b128 v[140:143], v140 offset:3072
	ds_read_b128 v[144:147], v170
	ds_read_b128 v[148:151], v170 offset:1024
	ds_read_b128 v[180:183], v170 offset:2048
	ds_read_b128 v[188:191], v170 offset:3072
	s_add_u32 s50, s50, 0x40000
	s_addc_u32 s51, s51, 0
	s_mov_b32 m0, s54
	v_lshl_add_u64 v[206:207], s[50:51], 0, v[152:153]
	ds_read_b128 v[196:199], v195 offset:32768
	ds_read_b128 v[202:205], v195 offset:33792
	ds_read_b128 v[210:213], v195 offset:34816
	ds_read_b128 v[214:217], v195 offset:35840
	ds_read_b128 v[218:221], v195 offset:36864
	ds_read_b128 v[222:225], v195 offset:37888
	ds_read_b128 v[226:229], v195 offset:38912
	ds_read_b128 v[230:233], v195 offset:39936
	global_load_lds_dwordx4 v[206:207], off
	v_lshl_add_u64 v[206:207], s[50:51], 0, v[156:157]
	s_mov_b32 m0, s55
	s_nop 0
	global_load_lds_dwordx4 v[206:207], off
	s_waitcnt vmcnt(8)
	s_waitcnt lgkmcnt(0)
	s_barrier
	s_setprio 1
	s_waitcnt lgkmcnt(0)
	v_mfma_f32_16x16x32_bf16 v[124:127], v[128:131], v[196:199], v[124:127]
	v_mfma_f32_16x16x32_bf16 v[120:123], v[136:139], v[196:199], v[120:123]
	v_mfma_f32_16x16x32_bf16 v[108:111], v[128:131], v[210:213], v[108:111]
	v_mfma_f32_16x16x32_bf16 v[104:107], v[136:139], v[210:213], v[104:107]
	v_mfma_f32_16x16x32_bf16 v[92:95], v[128:131], v[218:221], v[92:95]
	v_mfma_f32_16x16x32_bf16 v[88:91], v[136:139], v[218:221], v[88:91]
	v_mfma_f32_16x16x32_bf16 v[76:79], v[128:131], v[226:229], v[76:79]
	v_mfma_f32_16x16x32_bf16 v[72:75], v[136:139], v[226:229], v[72:75]
	v_mfma_f32_16x16x32_bf16 v[124:127], v[132:135], v[202:205], v[124:127]
	v_mfma_f32_16x16x32_bf16 v[120:123], v[140:143], v[202:205], v[120:123]
	v_mfma_f32_16x16x32_bf16 v[108:111], v[132:135], v[214:217], v[108:111]
	v_mfma_f32_16x16x32_bf16 v[104:107], v[140:143], v[214:217], v[104:107]
	v_mfma_f32_16x16x32_bf16 v[92:95], v[132:135], v[222:225], v[92:95]
	v_mfma_f32_16x16x32_bf16 v[88:91], v[140:143], v[222:225], v[88:91]
	v_mfma_f32_16x16x32_bf16 v[76:79], v[132:135], v[230:233], v[76:79]
	v_mfma_f32_16x16x32_bf16 v[72:75], v[140:143], v[230:233], v[72:75]
	v_mfma_f32_16x16x32_bf16 v[116:119], v[144:147], v[196:199], v[116:119]
	v_mfma_f32_16x16x32_bf16 v[112:115], v[180:183], v[196:199], v[112:115]
	v_mfma_f32_16x16x32_bf16 v[100:103], v[144:147], v[210:213], v[100:103]
	v_mfma_f32_16x16x32_bf16 v[96:99], v[180:183], v[210:213], v[96:99]
	v_mfma_f32_16x16x32_bf16 v[84:87], v[144:147], v[218:221], v[84:87]
	v_mfma_f32_16x16x32_bf16 v[80:83], v[180:183], v[218:221], v[80:83]
	v_mfma_f32_16x16x32_bf16 v[68:71], v[144:147], v[226:229], v[68:71]
	v_mfma_f32_16x16x32_bf16 v[64:67], v[180:183], v[226:229], v[64:67]
	v_mfma_f32_16x16x32_bf16 v[116:119], v[148:151], v[202:205], v[116:119]
	v_mfma_f32_16x16x32_bf16 v[112:115], v[188:191], v[202:205], v[112:115]
	v_mfma_f32_16x16x32_bf16 v[100:103], v[148:151], v[214:217], v[100:103]
	v_mfma_f32_16x16x32_bf16 v[96:99], v[188:191], v[214:217], v[96:99]
	v_mfma_f32_16x16x32_bf16 v[84:87], v[148:151], v[222:225], v[84:87]
	v_mfma_f32_16x16x32_bf16 v[80:83], v[188:191], v[222:225], v[80:83]
	v_mfma_f32_16x16x32_bf16 v[68:71], v[148:151], v[230:233], v[68:71]
	v_mfma_f32_16x16x32_bf16 v[64:67], v[188:191], v[230:233], v[64:67]
	s_setprio 0
	s_barrier
	s_add_i32 s50, s67, s52
	v_lshl_add_u64 v[168:169], v[168:169], 0, s[20:21]
	s_mov_b32 m0, s50
	ds_read_b128 v[196:199], v195 offset:49152
	ds_read_b128 v[202:205], v195 offset:50176
	ds_read_b128 v[210:213], v195 offset:51200
	ds_read_b128 v[214:217], v195 offset:52224
	ds_read_b128 v[218:221], v195 offset:53248
	ds_read_b128 v[222:225], v195 offset:54272
	ds_read_b128 v[226:229], v195 offset:55296
	ds_read_b128 v[230:233], v195 offset:56320
	global_load_lds_dwordx4 v[168:169], off
	s_add_i32 m0, s50, 0x2000
	s_add_u32 s48, s48, 0x40080
	v_lshl_add_u64 v[168:169], v[176:177], 0, s[20:21]
	s_addc_u32 s49, s49, 0
	s_add_i32 s50, s68, s52
	global_load_lds_dwordx4 v[168:169], off
	v_lshl_add_u64 v[168:169], s[48:49], 0, v[154:155]
	s_mov_b32 m0, s50
	s_nop 0
	global_load_lds_dwordx4 v[168:169], off
	v_lshl_add_u64 v[168:169], s[48:49], 0, v[158:159]
	s_add_i32 m0, s50, 0x2000
	s_nop 0
	global_load_lds_dwordx4 v[168:169], off
	v_lshl_add_u64 v[168:169], v[184:185], 0, s[20:21]
	s_mov_b32 m0, s57
	s_nop 0
	global_load_lds_dwordx4 v[168:169], off
	v_lshl_add_u64 v[168:169], v[192:193], 0, s[20:21]
	s_mov_b32 m0, s58
	s_nop 0
	global_load_lds_dwordx4 v[168:169], off
	s_waitcnt vmcnt(8)
	s_waitcnt lgkmcnt(0)
	s_barrier
	s_setprio 1
	s_waitcnt lgkmcnt(0)
	v_mfma_f32_16x16x32_bf16 v[60:63], v[128:131], v[196:199], v[60:63]
	v_mfma_f32_16x16x32_bf16 v[56:59], v[136:139], v[196:199], v[56:59]
	v_mfma_f32_16x16x32_bf16 v[44:47], v[128:131], v[210:213], v[44:47]
	v_mfma_f32_16x16x32_bf16 v[40:43], v[136:139], v[210:213], v[40:43]
	v_mfma_f32_16x16x32_bf16 v[28:31], v[128:131], v[218:221], v[28:31]
	v_mfma_f32_16x16x32_bf16 v[24:27], v[136:139], v[218:221], v[24:27]
	v_mfma_f32_16x16x32_bf16 v[12:15], v[128:131], v[226:229], v[12:15]
	v_mfma_f32_16x16x32_bf16 v[8:11], v[136:139], v[226:229], v[8:11]
	v_mfma_f32_16x16x32_bf16 v[60:63], v[132:135], v[202:205], v[60:63]
	v_mfma_f32_16x16x32_bf16 v[56:59], v[140:143], v[202:205], v[56:59]
	v_mfma_f32_16x16x32_bf16 v[44:47], v[132:135], v[214:217], v[44:47]
	v_mfma_f32_16x16x32_bf16 v[40:43], v[140:143], v[214:217], v[40:43]
	v_mfma_f32_16x16x32_bf16 v[28:31], v[132:135], v[222:225], v[28:31]
	v_mfma_f32_16x16x32_bf16 v[24:27], v[140:143], v[222:225], v[24:27]
	v_mfma_f32_16x16x32_bf16 v[12:15], v[132:135], v[230:233], v[12:15]
	v_mfma_f32_16x16x32_bf16 v[8:11], v[140:143], v[230:233], v[8:11]
	v_mfma_f32_16x16x32_bf16 v[52:55], v[144:147], v[196:199], v[52:55]
	v_mfma_f32_16x16x32_bf16 v[48:51], v[180:183], v[196:199], v[48:51]
	v_mfma_f32_16x16x32_bf16 v[36:39], v[144:147], v[210:213], v[36:39]
	v_mfma_f32_16x16x32_bf16 v[32:35], v[180:183], v[210:213], v[32:35]
	v_mfma_f32_16x16x32_bf16 v[20:23], v[144:147], v[218:221], v[20:23]
	v_mfma_f32_16x16x32_bf16 v[16:19], v[180:183], v[218:221], v[16:19]
	v_mfma_f32_16x16x32_bf16 v[4:7], v[144:147], v[226:229], v[4:7]
	v_mfma_f32_16x16x32_bf16 v[0:3], v[180:183], v[226:229], v[0:3]
	v_mfma_f32_16x16x32_bf16 v[52:55], v[148:151], v[202:205], v[52:55]
	v_mfma_f32_16x16x32_bf16 v[48:51], v[188:191], v[202:205], v[48:51]
	v_mfma_f32_16x16x32_bf16 v[36:39], v[148:151], v[214:217], v[36:39]
	v_mfma_f32_16x16x32_bf16 v[32:35], v[188:191], v[214:217], v[32:35]
	v_mfma_f32_16x16x32_bf16 v[20:23], v[148:151], v[222:225], v[20:23]
	v_mfma_f32_16x16x32_bf16 v[16:19], v[188:191], v[222:225], v[16:19]
	v_mfma_f32_16x16x32_bf16 v[4:7], v[148:151], v[230:233], v[4:7]
	v_mfma_f32_16x16x32_bf16 v[0:3], v[188:191], v[230:233], v[0:3]
	s_setprio 0
	s_barrier
	s_add_i32 s66, s66, 2
	s_add_u32 s46, s46, 0x100
	s_addc_u32 s47, s47, 0
	s_add_u32 s64, s64, 0x100
	s_addc_u32 s65, s65, 0
	s_cmp_gt_u32 s66, 13
	s_cbranch_scc0 .LBB0_492
	s_and_b64 vcc, exec, s[22:23]
	s_cbranch_vccz .LBB0_495
	s_barrier

.LBB0_578:
	ds_read_b128 v[72:75], v206
	ds_read_b128 v[76:79], v206 offset:1024
	ds_read_b128 v[80:83], v206 offset:2048
	ds_read_b128 v[84:87], v206 offset:3072
	ds_read_b128 v[116:119], v207
	ds_read_b128 v[120:123], v207 offset:1024
	ds_read_b128 v[124:127], v207 offset:2048
	ds_read_b128 v[128:131], v207 offset:3072
	s_add_u32 s58, s56, 0x100
	s_addc_u32 s59, s57, 0
	s_cmp_eq_u32 s79, 12
	s_cselect_b32 s63, s47, s59
	s_cselect_b32 s62, s53, s58
	s_cselect_b32 s61, s45, s78
	s_cselect_b32 s60, s76, s77
	v_lshl_add_u64 v[220:221], s[56:57], 0, v[184:185]
	s_add_i32 m0, s43, 0xc000
	ds_read_b128 v[140:143], v209
	ds_read_b128 v[164:167], v209 offset:1024
	ds_read_b128 v[168:171], v209 offset:2048
	ds_read_b128 v[192:195], v209 offset:3072
	ds_read_b128 v[196:199], v209 offset:4096
	ds_read_b128 v[200:203], v209 offset:5120
	ds_read_b128 v[212:215], v209 offset:6144
	ds_read_b128 v[216:219], v209 offset:7168
	global_load_lds_dwordx4 v[220:221], off
	v_lshl_add_u64 v[220:221], s[56:57], 0, v[186:187]
	s_add_i32 m0, s43, 0xe000
	s_nop 0
	global_load_lds_dwordx4 v[220:221], off
	s_waitcnt vmcnt(8)
	s_waitcnt lgkmcnt(0)
	s_barrier
	s_setprio 1
	s_waitcnt lgkmcnt(0)
	v_mfma_f32_16x16x32_bf16 v[160:163], v[72:75], v[140:143], v[160:163]
	v_mfma_f32_16x16x32_bf16 v[108:111], v[80:83], v[140:143], v[108:111]
	v_mfma_f32_16x16x32_bf16 v[156:159], v[72:75], v[168:171], v[156:159]
	v_mfma_f32_16x16x32_bf16 v[104:107], v[80:83], v[168:171], v[104:107]
	v_mfma_f32_16x16x32_bf16 v[144:147], v[72:75], v[196:199], v[144:147]
	v_mfma_f32_16x16x32_bf16 v[92:95], v[80:83], v[196:199], v[92:95]
	v_mfma_f32_16x16x32_bf16 v[152:155], v[72:75], v[212:215], v[152:155]
	v_mfma_f32_16x16x32_bf16 v[100:103], v[80:83], v[212:215], v[100:103]
	v_mfma_f32_16x16x32_bf16 v[160:163], v[76:79], v[164:167], v[160:163]
	v_mfma_f32_16x16x32_bf16 v[108:111], v[84:87], v[164:167], v[108:111]
	v_mfma_f32_16x16x32_bf16 v[156:159], v[76:79], v[192:195], v[156:159]
	v_mfma_f32_16x16x32_bf16 v[104:107], v[84:87], v[192:195], v[104:107]
	v_mfma_f32_16x16x32_bf16 v[144:147], v[76:79], v[200:203], v[144:147]
	v_mfma_f32_16x16x32_bf16 v[92:95], v[84:87], v[200:203], v[92:95]
	v_mfma_f32_16x16x32_bf16 v[152:155], v[76:79], v[216:219], v[152:155]
	v_mfma_f32_16x16x32_bf16 v[100:103], v[84:87], v[216:219], v[100:103]
	v_mfma_f32_16x16x32_bf16 v[148:151], v[116:119], v[140:143], v[148:151]
	v_mfma_f32_16x16x32_bf16 v[96:99], v[124:127], v[140:143], v[96:99]
	v_mfma_f32_16x16x32_bf16 v[136:139], v[116:119], v[168:171], v[136:139]
	v_mfma_f32_16x16x32_bf16 v[88:91], v[124:127], v[168:171], v[88:91]
	v_mfma_f32_16x16x32_bf16 v[132:135], v[116:119], v[196:199], v[132:135]
	v_mfma_f32_16x16x32_bf16 v[68:71], v[124:127], v[196:199], v[68:71]
	v_mfma_f32_16x16x32_bf16 v[112:115], v[116:119], v[212:215], v[112:115]
	v_mfma_f32_16x16x32_bf16 v[64:67], v[124:127], v[212:215], v[64:67]
	v_mfma_f32_16x16x32_bf16 v[148:151], v[120:123], v[164:167], v[148:151]
	v_mfma_f32_16x16x32_bf16 v[96:99], v[128:131], v[164:167], v[96:99]
	v_mfma_f32_16x16x32_bf16 v[136:139], v[120:123], v[192:195], v[136:139]
	v_mfma_f32_16x16x32_bf16 v[88:91], v[128:131], v[192:195], v[88:91]
	v_mfma_f32_16x16x32_bf16 v[132:135], v[120:123], v[200:203], v[132:135]
	v_mfma_f32_16x16x32_bf16 v[68:71], v[128:131], v[200:203], v[68:71]
	v_mfma_f32_16x16x32_bf16 v[112:115], v[120:123], v[216:219], v[112:115]
	v_mfma_f32_16x16x32_bf16 v[64:67], v[128:131], v[216:219], v[64:67]
	s_setprio 0
	s_barrier
	s_add_i32 s56, s73, s41
	v_lshl_add_u64 v[220:221], s[60:61], 0, v[176:177]
	s_mov_b32 m0, s56
	ds_read_b128 v[140:143], v209 offset:16384
	ds_read_b128 v[164:167], v209 offset:17408
	ds_read_b128 v[168:171], v209 offset:18432
	ds_read_b128 v[192:195], v209 offset:19456
	ds_read_b128 v[196:199], v209 offset:20480
	ds_read_b128 v[200:203], v209 offset:21504
	ds_read_b128 v[212:215], v209 offset:22528
	ds_read_b128 v[216:219], v209 offset:23552
	global_load_lds_dwordx4 v[220:221], off
	s_add_i32 m0, s56, 0x2000
	s_add_u32 s56, s60, 0x40000
	v_lshl_add_u64 v[222:223], s[60:61], 0, v[180:181]
	s_addc_u32 s57, s61, 0
	s_add_i32 s80, s74, s41
	global_load_lds_dwordx4 v[222:223], off
	v_lshl_add_u64 v[224:225], s[56:57], 0, v[176:177]
	s_mov_b32 m0, s80
	v_lshl_add_u64 v[226:227], s[62:63], 0, v[178:179]
	global_load_lds_dwordx4 v[224:225], off
	v_lshl_add_u64 v[224:225], s[56:57], 0, v[180:181]
	s_add_i32 m0, s80, 0x2000
	s_nop 0
	global_load_lds_dwordx4 v[224:225], off
	v_lshl_add_u64 v[224:225], s[62:63], 0, v[174:175]
	s_mov_b32 m0, s43
	s_nop 0
	global_load_lds_dwordx4 v[224:225], off
	s_mov_b32 m0, s55
	s_nop 0
	global_load_lds_dwordx4 v[226:227], off
	s_waitcnt vmcnt(8)
	s_waitcnt lgkmcnt(0)
	s_barrier
	s_setprio 1
	s_waitcnt lgkmcnt(0)
	v_mfma_f32_16x16x32_bf16 v[60:63], v[72:75], v[140:143], v[60:63]
	v_mfma_f32_16x16x32_bf16 v[28:31], v[80:83], v[140:143], v[28:31]
	v_mfma_f32_16x16x32_bf16 v[56:59], v[72:75], v[168:171], v[56:59]
	v_mfma_f32_16x16x32_bf16 v[24:27], v[80:83], v[168:171], v[24:27]
	v_mfma_f32_16x16x32_bf16 v[44:47], v[72:75], v[196:199], v[44:47]
	v_mfma_f32_16x16x32_bf16 v[12:15], v[80:83], v[196:199], v[12:15]
	v_mfma_f32_16x16x32_bf16 v[52:55], v[72:75], v[212:215], v[52:55]
	v_mfma_f32_16x16x32_bf16 v[20:23], v[80:83], v[212:215], v[20:23]
	v_mfma_f32_16x16x32_bf16 v[60:63], v[76:79], v[164:167], v[60:63]
	v_mfma_f32_16x16x32_bf16 v[28:31], v[84:87], v[164:167], v[28:31]
	v_mfma_f32_16x16x32_bf16 v[56:59], v[76:79], v[192:195], v[56:59]
	v_mfma_f32_16x16x32_bf16 v[24:27], v[84:87], v[192:195], v[24:27]
	v_mfma_f32_16x16x32_bf16 v[44:47], v[76:79], v[200:203], v[44:47]
	v_mfma_f32_16x16x32_bf16 v[12:15], v[84:87], v[200:203], v[12:15]
	v_mfma_f32_16x16x32_bf16 v[52:55], v[76:79], v[216:219], v[52:55]
	v_mfma_f32_16x16x32_bf16 v[20:23], v[84:87], v[216:219], v[20:23]
	v_mfma_f32_16x16x32_bf16 v[48:51], v[116:119], v[140:143], v[48:51]
	v_mfma_f32_16x16x32_bf16 v[16:19], v[124:127], v[140:143], v[16:19]
	v_mfma_f32_16x16x32_bf16 v[40:43], v[116:119], v[168:171], v[40:43]
	v_mfma_f32_16x16x32_bf16 v[8:11], v[124:127], v[168:171], v[8:11]
	v_mfma_f32_16x16x32_bf16 v[36:39], v[116:119], v[196:199], v[36:39]
	v_mfma_f32_16x16x32_bf16 v[4:7], v[124:127], v[196:199], v[4:7]
	v_mfma_f32_16x16x32_bf16 v[32:35], v[116:119], v[212:215], v[32:35]
	v_mfma_f32_16x16x32_bf16 v[0:3], v[124:127], v[212:215], v[0:3]
	v_mfma_f32_16x16x32_bf16 v[48:51], v[120:123], v[164:167], v[48:51]
	v_mfma_f32_16x16x32_bf16 v[16:19], v[128:131], v[164:167], v[16:19]
	v_mfma_f32_16x16x32_bf16 v[40:43], v[120:123], v[192:195], v[40:43]
	v_mfma_f32_16x16x32_bf16 v[8:11], v[128:131], v[192:195], v[8:11]
	v_mfma_f32_16x16x32_bf16 v[36:39], v[120:123], v[200:203], v[36:39]
	v_mfma_f32_16x16x32_bf16 v[4:7], v[128:131], v[200:203], v[4:7]
	v_mfma_f32_16x16x32_bf16 v[32:35], v[120:123], v[216:219], v[32:35]
	v_mfma_f32_16x16x32_bf16 v[0:3], v[128:131], v[216:219], v[0:3]
	s_setprio 0
	s_barrier
	s_add_i32 s80, 0, 0x18000
	s_add_i32 s81, 0, 0x1c000
	v_add_u32_e32 v84, s80, v204
	v_add_u32_e32 v128, s81, v204
	ds_read_b128 v[72:75], v84
	ds_read_b128 v[76:79], v84 offset:1024
	ds_read_b128 v[80:83], v84 offset:2048
	ds_read_b128 v[84:87], v84 offset:3072
	ds_read_b128 v[116:119], v128
	ds_read_b128 v[120:123], v128 offset:1024
	ds_read_b128 v[124:127], v128 offset:2048
	ds_read_b128 v[128:131], v128 offset:3072
	s_add_u32 s56, s62, 0x40000
	s_addc_u32 s57, s63, 0
	s_mov_b32 m0, s64
	v_lshl_add_u64 v[228:229], s[56:57], 0, v[174:175]
	ds_read_b128 v[140:143], v209 offset:32768
	ds_read_b128 v[164:167], v209 offset:33792
	ds_read_b128 v[168:171], v209 offset:34816
	ds_read_b128 v[192:195], v209 offset:35840
	ds_read_b128 v[196:199], v209 offset:36864
	ds_read_b128 v[200:203], v209 offset:37888
	ds_read_b128 v[212:215], v209 offset:38912
	ds_read_b128 v[216:219], v209 offset:39936
	global_load_lds_dwordx4 v[228:229], off
	v_lshl_add_u64 v[228:229], s[56:57], 0, v[178:179]
	s_mov_b32 m0, s65
	s_nop 0
	global_load_lds_dwordx4 v[228:229], off
	s_waitcnt vmcnt(8)
	s_waitcnt lgkmcnt(0)
	s_barrier
	s_setprio 1
	s_waitcnt lgkmcnt(0)
	v_mfma_f32_16x16x32_bf16 v[160:163], v[72:75], v[140:143], v[160:163]
	v_mfma_f32_16x16x32_bf16 v[108:111], v[80:83], v[140:143], v[108:111]
	v_mfma_f32_16x16x32_bf16 v[156:159], v[72:75], v[168:171], v[156:159]
	v_mfma_f32_16x16x32_bf16 v[104:107], v[80:83], v[168:171], v[104:107]
	v_mfma_f32_16x16x32_bf16 v[144:147], v[72:75], v[196:199], v[144:147]
	v_mfma_f32_16x16x32_bf16 v[92:95], v[80:83], v[196:199], v[92:95]
	v_mfma_f32_16x16x32_bf16 v[152:155], v[72:75], v[212:215], v[152:155]
	v_mfma_f32_16x16x32_bf16 v[100:103], v[80:83], v[212:215], v[100:103]
	v_mfma_f32_16x16x32_bf16 v[160:163], v[76:79], v[164:167], v[160:163]
	v_mfma_f32_16x16x32_bf16 v[108:111], v[84:87], v[164:167], v[108:111]
	v_mfma_f32_16x16x32_bf16 v[156:159], v[76:79], v[192:195], v[156:159]
	v_mfma_f32_16x16x32_bf16 v[104:107], v[84:87], v[192:195], v[104:107]
	v_mfma_f32_16x16x32_bf16 v[144:147], v[76:79], v[200:203], v[144:147]
	v_mfma_f32_16x16x32_bf16 v[92:95], v[84:87], v[200:203], v[92:95]
	v_mfma_f32_16x16x32_bf16 v[152:155], v[76:79], v[216:219], v[152:155]
	v_mfma_f32_16x16x32_bf16 v[100:103], v[84:87], v[216:219], v[100:103]
	v_mfma_f32_16x16x32_bf16 v[148:151], v[116:119], v[140:143], v[148:151]
	v_mfma_f32_16x16x32_bf16 v[96:99], v[124:127], v[140:143], v[96:99]
	v_mfma_f32_16x16x32_bf16 v[136:139], v[116:119], v[168:171], v[136:139]
	v_mfma_f32_16x16x32_bf16 v[88:91], v[124:127], v[168:171], v[88:91]
	v_mfma_f32_16x16x32_bf16 v[132:135], v[116:119], v[196:199], v[132:135]
	v_mfma_f32_16x16x32_bf16 v[68:71], v[124:127], v[196:199], v[68:71]
	v_mfma_f32_16x16x32_bf16 v[112:115], v[116:119], v[212:215], v[112:115]
	v_mfma_f32_16x16x32_bf16 v[64:67], v[124:127], v[212:215], v[64:67]
	v_mfma_f32_16x16x32_bf16 v[148:151], v[120:123], v[164:167], v[148:151]
	v_mfma_f32_16x16x32_bf16 v[96:99], v[128:131], v[164:167], v[96:99]
	v_mfma_f32_16x16x32_bf16 v[136:139], v[120:123], v[192:195], v[136:139]
	v_mfma_f32_16x16x32_bf16 v[88:91], v[128:131], v[192:195], v[88:91]
	v_mfma_f32_16x16x32_bf16 v[132:135], v[120:123], v[200:203], v[132:135]
	v_mfma_f32_16x16x32_bf16 v[68:71], v[128:131], v[200:203], v[68:71]
	v_mfma_f32_16x16x32_bf16 v[112:115], v[120:123], v[216:219], v[112:115]
	v_mfma_f32_16x16x32_bf16 v[64:67], v[128:131], v[216:219], v[64:67]
	s_setprio 0
	s_barrier
	s_add_i32 s56, s80, s41
	v_lshl_add_u64 v[220:221], v[220:221], 0, s[22:23]
	s_mov_b32 m0, s56
	ds_read_b128 v[140:143], v209 offset:49152
	ds_read_b128 v[164:167], v209 offset:50176
	ds_read_b128 v[168:171], v209 offset:51200
	ds_read_b128 v[192:195], v209 offset:52224
	ds_read_b128 v[196:199], v209 offset:53248
	ds_read_b128 v[200:203], v209 offset:54272
	ds_read_b128 v[212:215], v209 offset:55296
	ds_read_b128 v[216:219], v209 offset:56320
	global_load_lds_dwordx4 v[220:221], off
	s_add_i32 m0, s56, 0x2000
	s_add_u32 s56, s60, 0x40080
	v_lshl_add_u64 v[220:221], v[222:223], 0, s[22:23]
	s_addc_u32 s57, s61, 0
	s_add_i32 s60, s81, s41
	global_load_lds_dwordx4 v[220:221], off
	v_lshl_add_u64 v[220:221], s[56:57], 0, v[176:177]
	s_mov_b32 m0, s60
	s_nop 0
	global_load_lds_dwordx4 v[220:221], off
	v_lshl_add_u64 v[220:221], s[56:57], 0, v[180:181]
	s_add_i32 m0, s60, 0x2000
	s_nop 0
	global_load_lds_dwordx4 v[220:221], off
	v_lshl_add_u64 v[220:221], v[224:225], 0, s[22:23]
	s_mov_b32 m0, s69
	s_nop 0
	global_load_lds_dwordx4 v[220:221], off
	v_lshl_add_u64 v[220:221], v[226:227], 0, s[22:23]
	s_mov_b32 m0, s70
	s_nop 0
	global_load_lds_dwordx4 v[220:221], off
	s_waitcnt vmcnt(8)
	s_waitcnt lgkmcnt(0)
	s_barrier
	s_setprio 1
	s_waitcnt lgkmcnt(0)
	v_mfma_f32_16x16x32_bf16 v[60:63], v[72:75], v[140:143], v[60:63]
	v_mfma_f32_16x16x32_bf16 v[28:31], v[80:83], v[140:143], v[28:31]
	v_mfma_f32_16x16x32_bf16 v[56:59], v[72:75], v[168:171], v[56:59]
	v_mfma_f32_16x16x32_bf16 v[24:27], v[80:83], v[168:171], v[24:27]
	v_mfma_f32_16x16x32_bf16 v[44:47], v[72:75], v[196:199], v[44:47]
	v_mfma_f32_16x16x32_bf16 v[12:15], v[80:83], v[196:199], v[12:15]
	v_mfma_f32_16x16x32_bf16 v[52:55], v[72:75], v[212:215], v[52:55]
	v_mfma_f32_16x16x32_bf16 v[20:23], v[80:83], v[212:215], v[20:23]
	v_mfma_f32_16x16x32_bf16 v[60:63], v[76:79], v[164:167], v[60:63]
	v_mfma_f32_16x16x32_bf16 v[28:31], v[84:87], v[164:167], v[28:31]
	v_mfma_f32_16x16x32_bf16 v[56:59], v[76:79], v[192:195], v[56:59]
	v_mfma_f32_16x16x32_bf16 v[24:27], v[84:87], v[192:195], v[24:27]
	v_mfma_f32_16x16x32_bf16 v[44:47], v[76:79], v[200:203], v[44:47]
	v_mfma_f32_16x16x32_bf16 v[12:15], v[84:87], v[200:203], v[12:15]
	v_mfma_f32_16x16x32_bf16 v[52:55], v[76:79], v[216:219], v[52:55]
	v_mfma_f32_16x16x32_bf16 v[20:23], v[84:87], v[216:219], v[20:23]
	v_mfma_f32_16x16x32_bf16 v[48:51], v[116:119], v[140:143], v[48:51]
	v_mfma_f32_16x16x32_bf16 v[16:19], v[124:127], v[140:143], v[16:19]
	v_mfma_f32_16x16x32_bf16 v[40:43], v[116:119], v[168:171], v[40:43]
	v_mfma_f32_16x16x32_bf16 v[8:11], v[124:127], v[168:171], v[8:11]
	v_mfma_f32_16x16x32_bf16 v[36:39], v[116:119], v[196:199], v[36:39]
	v_mfma_f32_16x16x32_bf16 v[4:7], v[124:127], v[196:199], v[4:7]
	v_mfma_f32_16x16x32_bf16 v[32:35], v[116:119], v[212:215], v[32:35]
	v_mfma_f32_16x16x32_bf16 v[0:3], v[124:127], v[212:215], v[0:3]
	v_mfma_f32_16x16x32_bf16 v[48:51], v[120:123], v[164:167], v[48:51]
	v_mfma_f32_16x16x32_bf16 v[16:19], v[128:131], v[164:167], v[16:19]
	v_mfma_f32_16x16x32_bf16 v[40:43], v[120:123], v[192:195], v[40:43]
	v_mfma_f32_16x16x32_bf16 v[8:11], v[128:131], v[192:195], v[8:11]
	v_mfma_f32_16x16x32_bf16 v[36:39], v[120:123], v[200:203], v[36:39]
	v_mfma_f32_16x16x32_bf16 v[4:7], v[128:131], v[200:203], v[4:7]
	v_mfma_f32_16x16x32_bf16 v[32:35], v[120:123], v[216:219], v[32:35]
	v_mfma_f32_16x16x32_bf16 v[0:3], v[128:131], v[216:219], v[0:3]
	s_setprio 0
	s_barrier
	s_add_i32 s79, s79, 2
	s_add_u32 s77, s77, 0x100
	s_addc_u32 s78, s78, 0
	s_cmp_gt_u32 s79, 13
	s_mov_b64 s[56:57], s[58:59]
	s_cbranch_scc0 .LBB0_578
	s_and_b64 vcc, exec, s[24:25]
	s_cbranch_vccz .LBB0_581
	s_barrier

.LBB0_741:
	ds_read_b128 v[128:131], v194
	ds_read_b128 v[132:135], v194 offset:1024
	ds_read_b128 v[136:139], v194 offset:2048
	ds_read_b128 v[140:143], v194 offset:3072
	ds_read_b128 v[144:147], v195
	ds_read_b128 v[148:151], v195 offset:1024
	ds_read_b128 v[168:171], v195 offset:2048
	ds_read_b128 v[174:177], v195 offset:3072
	s_add_u32 s38, s36, 0x100
	s_addc_u32 s39, s37, 0
	s_cmp_eq_u32 s62, 40
	s_cselect_b32 s43, s11, s39
	s_cselect_b32 s42, s10, s38
	s_cselect_b32 s41, s25, s61
	s_cselect_b32 s40, s24, s60
	v_lshl_add_u64 v[190:191], s[36:37], 0, v[160:161]
	s_add_i32 m0, s45, 0xc000
	ds_read_b128 v[178:181], v196
	ds_read_b128 v[182:185], v196 offset:1024
	ds_read_b128 v[186:189], v196 offset:2048
	ds_read_b128 v[198:201], v196 offset:3072
	ds_read_b128 v[202:205], v196 offset:4096
	ds_read_b128 v[210:213], v196 offset:5120
	ds_read_b128 v[214:217], v196 offset:6144
	ds_read_b128 v[218:221], v196 offset:7168
	global_load_lds_dwordx4 v[190:191], off
	v_lshl_add_u64 v[190:191], s[36:37], 0, v[162:163]
	s_add_i32 m0, s45, 0xe000
	s_nop 0
	global_load_lds_dwordx4 v[190:191], off
	s_waitcnt vmcnt(8)
	s_waitcnt lgkmcnt(0)
	s_barrier
	s_setprio 1
	s_waitcnt lgkmcnt(0)
	v_mfma_f32_16x16x32_bf16 v[124:127], v[128:131], v[178:181], v[124:127]
	v_mfma_f32_16x16x32_bf16 v[120:123], v[136:139], v[178:181], v[120:123]
	v_mfma_f32_16x16x32_bf16 v[108:111], v[128:131], v[186:189], v[108:111]
	v_mfma_f32_16x16x32_bf16 v[104:107], v[136:139], v[186:189], v[104:107]
	v_mfma_f32_16x16x32_bf16 v[92:95], v[128:131], v[202:205], v[92:95]
	v_mfma_f32_16x16x32_bf16 v[88:91], v[136:139], v[202:205], v[88:91]
	v_mfma_f32_16x16x32_bf16 v[76:79], v[128:131], v[214:217], v[76:79]
	v_mfma_f32_16x16x32_bf16 v[72:75], v[136:139], v[214:217], v[72:75]
	v_mfma_f32_16x16x32_bf16 v[124:127], v[132:135], v[182:185], v[124:127]
	v_mfma_f32_16x16x32_bf16 v[120:123], v[140:143], v[182:185], v[120:123]
	v_mfma_f32_16x16x32_bf16 v[108:111], v[132:135], v[198:201], v[108:111]
	v_mfma_f32_16x16x32_bf16 v[104:107], v[140:143], v[198:201], v[104:107]
	v_mfma_f32_16x16x32_bf16 v[92:95], v[132:135], v[210:213], v[92:95]
	v_mfma_f32_16x16x32_bf16 v[88:91], v[140:143], v[210:213], v[88:91]
	v_mfma_f32_16x16x32_bf16 v[76:79], v[132:135], v[218:221], v[76:79]
	v_mfma_f32_16x16x32_bf16 v[72:75], v[140:143], v[218:221], v[72:75]
	v_mfma_f32_16x16x32_bf16 v[116:119], v[144:147], v[178:181], v[116:119]
	v_mfma_f32_16x16x32_bf16 v[112:115], v[168:171], v[178:181], v[112:115]
	v_mfma_f32_16x16x32_bf16 v[100:103], v[144:147], v[186:189], v[100:103]
	v_mfma_f32_16x16x32_bf16 v[96:99], v[168:171], v[186:189], v[96:99]
	v_mfma_f32_16x16x32_bf16 v[84:87], v[144:147], v[202:205], v[84:87]
	v_mfma_f32_16x16x32_bf16 v[80:83], v[168:171], v[202:205], v[80:83]
	v_mfma_f32_16x16x32_bf16 v[68:71], v[144:147], v[214:217], v[68:71]
	v_mfma_f32_16x16x32_bf16 v[64:67], v[168:171], v[214:217], v[64:67]
	v_mfma_f32_16x16x32_bf16 v[116:119], v[148:151], v[182:185], v[116:119]
	v_mfma_f32_16x16x32_bf16 v[112:115], v[174:177], v[182:185], v[112:115]
	v_mfma_f32_16x16x32_bf16 v[100:103], v[148:151], v[198:201], v[100:103]
	v_mfma_f32_16x16x32_bf16 v[96:99], v[174:177], v[198:201], v[96:99]
	v_mfma_f32_16x16x32_bf16 v[84:87], v[148:151], v[210:213], v[84:87]
	v_mfma_f32_16x16x32_bf16 v[80:83], v[174:177], v[210:213], v[80:83]
	v_mfma_f32_16x16x32_bf16 v[68:71], v[148:151], v[218:221], v[68:71]
	v_mfma_f32_16x16x32_bf16 v[64:67], v[174:177], v[218:221], v[64:67]
	s_setprio 0
	s_barrier
	s_add_i32 s36, s54, s44
	v_lshl_add_u64 v[190:191], s[40:41], 0, v[154:155]
	s_mov_b32 m0, s36
	ds_read_b128 v[178:181], v196 offset:16384
	ds_read_b128 v[182:185], v196 offset:17408
	ds_read_b128 v[186:189], v196 offset:18432
	ds_read_b128 v[198:201], v196 offset:19456
	ds_read_b128 v[202:205], v196 offset:20480
	ds_read_b128 v[210:213], v196 offset:21504
	ds_read_b128 v[214:217], v196 offset:22528
	ds_read_b128 v[218:221], v196 offset:23552
	global_load_lds_dwordx4 v[190:191], off
	s_add_i32 m0, s36, 0x2000
	s_add_u32 s36, s40, 0xb0000
	v_lshl_add_u64 v[206:207], s[40:41], 0, v[158:159]
	s_addc_u32 s37, s41, 0
	s_add_i32 s63, s55, s44
	global_load_lds_dwordx4 v[206:207], off
	v_lshl_add_u64 v[222:223], s[36:37], 0, v[154:155]
	s_mov_b32 m0, s63
	v_lshl_add_u64 v[224:225], s[42:43], 0, v[156:157]
	global_load_lds_dwordx4 v[222:223], off
	v_lshl_add_u64 v[222:223], s[36:37], 0, v[158:159]
	s_add_i32 m0, s63, 0x2000
	s_nop 0
	global_load_lds_dwordx4 v[222:223], off
	v_lshl_add_u64 v[222:223], s[42:43], 0, v[152:153]
	s_mov_b32 m0, s45
	s_nop 0
	global_load_lds_dwordx4 v[222:223], off
	s_mov_b32 m0, s46
	s_nop 0
	global_load_lds_dwordx4 v[224:225], off
	s_waitcnt vmcnt(8)
	s_waitcnt lgkmcnt(0)
	s_barrier
	s_setprio 1
	s_waitcnt lgkmcnt(0)
	v_mfma_f32_16x16x32_bf16 v[60:63], v[128:131], v[178:181], v[60:63]
	v_mfma_f32_16x16x32_bf16 v[56:59], v[136:139], v[178:181], v[56:59]
	v_mfma_f32_16x16x32_bf16 v[44:47], v[128:131], v[186:189], v[44:47]
	v_mfma_f32_16x16x32_bf16 v[40:43], v[136:139], v[186:189], v[40:43]
	v_mfma_f32_16x16x32_bf16 v[28:31], v[128:131], v[202:205], v[28:31]
	v_mfma_f32_16x16x32_bf16 v[24:27], v[136:139], v[202:205], v[24:27]
	v_mfma_f32_16x16x32_bf16 v[12:15], v[128:131], v[214:217], v[12:15]
	v_mfma_f32_16x16x32_bf16 v[8:11], v[136:139], v[214:217], v[8:11]
	v_mfma_f32_16x16x32_bf16 v[60:63], v[132:135], v[182:185], v[60:63]
	v_mfma_f32_16x16x32_bf16 v[56:59], v[140:143], v[182:185], v[56:59]
	v_mfma_f32_16x16x32_bf16 v[44:47], v[132:135], v[198:201], v[44:47]
	v_mfma_f32_16x16x32_bf16 v[40:43], v[140:143], v[198:201], v[40:43]
	v_mfma_f32_16x16x32_bf16 v[28:31], v[132:135], v[210:213], v[28:31]
	v_mfma_f32_16x16x32_bf16 v[24:27], v[140:143], v[210:213], v[24:27]
	v_mfma_f32_16x16x32_bf16 v[12:15], v[132:135], v[218:221], v[12:15]
	v_mfma_f32_16x16x32_bf16 v[8:11], v[140:143], v[218:221], v[8:11]
	v_mfma_f32_16x16x32_bf16 v[52:55], v[144:147], v[178:181], v[52:55]
	v_mfma_f32_16x16x32_bf16 v[48:51], v[168:171], v[178:181], v[48:51]
	v_mfma_f32_16x16x32_bf16 v[36:39], v[144:147], v[186:189], v[36:39]
	v_mfma_f32_16x16x32_bf16 v[32:35], v[168:171], v[186:189], v[32:35]
	v_mfma_f32_16x16x32_bf16 v[20:23], v[144:147], v[202:205], v[20:23]
	v_mfma_f32_16x16x32_bf16 v[16:19], v[168:171], v[202:205], v[16:19]
	v_mfma_f32_16x16x32_bf16 v[4:7], v[144:147], v[214:217], v[4:7]
	v_mfma_f32_16x16x32_bf16 v[0:3], v[168:171], v[214:217], v[0:3]
	v_mfma_f32_16x16x32_bf16 v[52:55], v[148:151], v[182:185], v[52:55]
	v_mfma_f32_16x16x32_bf16 v[48:51], v[174:177], v[182:185], v[48:51]
	v_mfma_f32_16x16x32_bf16 v[36:39], v[148:151], v[198:201], v[36:39]
	v_mfma_f32_16x16x32_bf16 v[32:35], v[174:177], v[198:201], v[32:35]
	v_mfma_f32_16x16x32_bf16 v[20:23], v[148:151], v[210:213], v[20:23]
	v_mfma_f32_16x16x32_bf16 v[16:19], v[174:177], v[210:213], v[16:19]
	v_mfma_f32_16x16x32_bf16 v[4:7], v[148:151], v[218:221], v[4:7]
	v_mfma_f32_16x16x32_bf16 v[0:3], v[174:177], v[218:221], v[0:3]
	s_setprio 0
	s_barrier
	s_add_i32 s63, 0, 0x18000
	s_add_i32 s64, 0, 0x1c000
	v_add_u32_e32 v140, s63, v192
	v_add_u32_e32 v174, s64, v192
	ds_read_b128 v[128:131], v140
	ds_read_b128 v[132:135], v140 offset:1024
	ds_read_b128 v[136:139], v140 offset:2048
	ds_read_b128 v[140:143], v140 offset:3072
	ds_read_b128 v[144:147], v174
	ds_read_b128 v[148:151], v174 offset:1024
	ds_read_b128 v[168:171], v174 offset:2048
	ds_read_b128 v[174:177], v174 offset:3072
	s_add_u32 s36, s42, 0xb0000
	s_addc_u32 s37, s43, 0
	s_mov_b32 m0, s47
	v_lshl_add_u64 v[226:227], s[36:37], 0, v[152:153]
	ds_read_b128 v[178:181], v196 offset:32768
	ds_read_b128 v[182:185], v196 offset:33792
	ds_read_b128 v[186:189], v196 offset:34816
	ds_read_b128 v[198:201], v196 offset:35840
	ds_read_b128 v[202:205], v196 offset:36864
	ds_read_b128 v[210:213], v196 offset:37888
	ds_read_b128 v[214:217], v196 offset:38912
	ds_read_b128 v[218:221], v196 offset:39936
	global_load_lds_dwordx4 v[226:227], off
	v_lshl_add_u64 v[226:227], s[36:37], 0, v[156:157]
	s_mov_b32 m0, s48
	s_nop 0
	global_load_lds_dwordx4 v[226:227], off
	s_waitcnt vmcnt(8)
	s_waitcnt lgkmcnt(0)
	s_barrier
	s_setprio 1
	s_waitcnt lgkmcnt(0)
	v_mfma_f32_16x16x32_bf16 v[124:127], v[128:131], v[178:181], v[124:127]
	v_mfma_f32_16x16x32_bf16 v[120:123], v[136:139], v[178:181], v[120:123]
	v_mfma_f32_16x16x32_bf16 v[108:111], v[128:131], v[186:189], v[108:111]
	v_mfma_f32_16x16x32_bf16 v[104:107], v[136:139], v[186:189], v[104:107]
	v_mfma_f32_16x16x32_bf16 v[92:95], v[128:131], v[202:205], v[92:95]
	v_mfma_f32_16x16x32_bf16 v[88:91], v[136:139], v[202:205], v[88:91]
	v_mfma_f32_16x16x32_bf16 v[76:79], v[128:131], v[214:217], v[76:79]
	v_mfma_f32_16x16x32_bf16 v[72:75], v[136:139], v[214:217], v[72:75]
	v_mfma_f32_16x16x32_bf16 v[124:127], v[132:135], v[182:185], v[124:127]
	v_mfma_f32_16x16x32_bf16 v[120:123], v[140:143], v[182:185], v[120:123]
	v_mfma_f32_16x16x32_bf16 v[108:111], v[132:135], v[198:201], v[108:111]
	v_mfma_f32_16x16x32_bf16 v[104:107], v[140:143], v[198:201], v[104:107]
	v_mfma_f32_16x16x32_bf16 v[92:95], v[132:135], v[210:213], v[92:95]
	v_mfma_f32_16x16x32_bf16 v[88:91], v[140:143], v[210:213], v[88:91]
	v_mfma_f32_16x16x32_bf16 v[76:79], v[132:135], v[218:221], v[76:79]
	v_mfma_f32_16x16x32_bf16 v[72:75], v[140:143], v[218:221], v[72:75]
	v_mfma_f32_16x16x32_bf16 v[116:119], v[144:147], v[178:181], v[116:119]
	v_mfma_f32_16x16x32_bf16 v[112:115], v[168:171], v[178:181], v[112:115]
	v_mfma_f32_16x16x32_bf16 v[100:103], v[144:147], v[186:189], v[100:103]
	v_mfma_f32_16x16x32_bf16 v[96:99], v[168:171], v[186:189], v[96:99]
	v_mfma_f32_16x16x32_bf16 v[84:87], v[144:147], v[202:205], v[84:87]
	v_mfma_f32_16x16x32_bf16 v[80:83], v[168:171], v[202:205], v[80:83]
	v_mfma_f32_16x16x32_bf16 v[68:71], v[144:147], v[214:217], v[68:71]
	v_mfma_f32_16x16x32_bf16 v[64:67], v[168:171], v[214:217], v[64:67]
	v_mfma_f32_16x16x32_bf16 v[116:119], v[148:151], v[182:185], v[116:119]
	v_mfma_f32_16x16x32_bf16 v[112:115], v[174:177], v[182:185], v[112:115]
	v_mfma_f32_16x16x32_bf16 v[100:103], v[148:151], v[198:201], v[100:103]
	v_mfma_f32_16x16x32_bf16 v[96:99], v[174:177], v[198:201], v[96:99]
	v_mfma_f32_16x16x32_bf16 v[84:87], v[148:151], v[210:213], v[84:87]
	v_mfma_f32_16x16x32_bf16 v[80:83], v[174:177], v[210:213], v[80:83]
	v_mfma_f32_16x16x32_bf16 v[68:71], v[148:151], v[218:221], v[68:71]
	v_mfma_f32_16x16x32_bf16 v[64:67], v[174:177], v[218:221], v[64:67]
	s_setprio 0
	s_barrier
	s_add_i32 s36, s63, s44
	v_lshl_add_u64 v[190:191], v[190:191], 0, s[20:21]
	s_mov_b32 m0, s36
	ds_read_b128 v[178:181], v196 offset:49152
	ds_read_b128 v[182:185], v196 offset:50176
	ds_read_b128 v[186:189], v196 offset:51200
	ds_read_b128 v[198:201], v196 offset:52224
	ds_read_b128 v[202:205], v196 offset:53248
	ds_read_b128 v[210:213], v196 offset:54272
	ds_read_b128 v[214:217], v196 offset:55296
	ds_read_b128 v[218:221], v196 offset:56320
	global_load_lds_dwordx4 v[190:191], off
	s_add_i32 m0, s36, 0x2000
	s_add_u32 s36, s40, 0xb0080
	v_lshl_add_u64 v[190:191], v[206:207], 0, s[20:21]
	s_addc_u32 s37, s41, 0
	s_add_i32 s40, s64, s44
	global_load_lds_dwordx4 v[190:191], off
	v_lshl_add_u64 v[190:191], s[36:37], 0, v[154:155]
	s_mov_b32 m0, s40
	s_nop 0
	global_load_lds_dwordx4 v[190:191], off
	v_lshl_add_u64 v[190:191], s[36:37], 0, v[158:159]
	s_add_i32 m0, s40, 0x2000
	s_nop 0
	global_load_lds_dwordx4 v[190:191], off
	v_lshl_add_u64 v[190:191], v[222:223], 0, s[20:21]
	s_mov_b32 m0, s50
	s_nop 0
	global_load_lds_dwordx4 v[190:191], off
	v_lshl_add_u64 v[190:191], v[224:225], 0, s[20:21]
	s_mov_b32 m0, s51
	s_nop 0
	global_load_lds_dwordx4 v[190:191], off
	s_waitcnt vmcnt(8)
	s_waitcnt lgkmcnt(0)
	s_barrier
	s_setprio 1
	s_waitcnt lgkmcnt(0)
	v_mfma_f32_16x16x32_bf16 v[60:63], v[128:131], v[178:181], v[60:63]
	v_mfma_f32_16x16x32_bf16 v[56:59], v[136:139], v[178:181], v[56:59]
	v_mfma_f32_16x16x32_bf16 v[44:47], v[128:131], v[186:189], v[44:47]
	v_mfma_f32_16x16x32_bf16 v[40:43], v[136:139], v[186:189], v[40:43]
	v_mfma_f32_16x16x32_bf16 v[28:31], v[128:131], v[202:205], v[28:31]
	v_mfma_f32_16x16x32_bf16 v[24:27], v[136:139], v[202:205], v[24:27]
	v_mfma_f32_16x16x32_bf16 v[12:15], v[128:131], v[214:217], v[12:15]
	v_mfma_f32_16x16x32_bf16 v[8:11], v[136:139], v[214:217], v[8:11]
	v_mfma_f32_16x16x32_bf16 v[60:63], v[132:135], v[182:185], v[60:63]
	v_mfma_f32_16x16x32_bf16 v[56:59], v[140:143], v[182:185], v[56:59]
	v_mfma_f32_16x16x32_bf16 v[44:47], v[132:135], v[198:201], v[44:47]
	v_mfma_f32_16x16x32_bf16 v[40:43], v[140:143], v[198:201], v[40:43]
	v_mfma_f32_16x16x32_bf16 v[28:31], v[132:135], v[210:213], v[28:31]
	v_mfma_f32_16x16x32_bf16 v[24:27], v[140:143], v[210:213], v[24:27]
	v_mfma_f32_16x16x32_bf16 v[12:15], v[132:135], v[218:221], v[12:15]
	v_mfma_f32_16x16x32_bf16 v[8:11], v[140:143], v[218:221], v[8:11]
	v_mfma_f32_16x16x32_bf16 v[52:55], v[144:147], v[178:181], v[52:55]
	v_mfma_f32_16x16x32_bf16 v[48:51], v[168:171], v[178:181], v[48:51]
	v_mfma_f32_16x16x32_bf16 v[36:39], v[144:147], v[186:189], v[36:39]
	v_mfma_f32_16x16x32_bf16 v[32:35], v[168:171], v[186:189], v[32:35]
	v_mfma_f32_16x16x32_bf16 v[20:23], v[144:147], v[202:205], v[20:23]
	v_mfma_f32_16x16x32_bf16 v[16:19], v[168:171], v[202:205], v[16:19]
	v_mfma_f32_16x16x32_bf16 v[4:7], v[144:147], v[214:217], v[4:7]
	v_mfma_f32_16x16x32_bf16 v[0:3], v[168:171], v[214:217], v[0:3]
	v_mfma_f32_16x16x32_bf16 v[52:55], v[148:151], v[182:185], v[52:55]
	v_mfma_f32_16x16x32_bf16 v[48:51], v[174:177], v[182:185], v[48:51]
	v_mfma_f32_16x16x32_bf16 v[36:39], v[148:151], v[198:201], v[36:39]
	v_mfma_f32_16x16x32_bf16 v[32:35], v[174:177], v[198:201], v[32:35]
	v_mfma_f32_16x16x32_bf16 v[20:23], v[148:151], v[210:213], v[20:23]
	v_mfma_f32_16x16x32_bf16 v[16:19], v[174:177], v[210:213], v[16:19]
	v_mfma_f32_16x16x32_bf16 v[4:7], v[148:151], v[218:221], v[4:7]
	v_mfma_f32_16x16x32_bf16 v[0:3], v[174:177], v[218:221], v[0:3]
	s_setprio 0
	s_barrier
	s_add_i32 s62, s62, 2
	s_add_u32 s60, s60, 0x100
	s_addc_u32 s61, s61, 0
	s_cmp_gt_u32 s62, 41
	s_mov_b64 s[36:37], s[38:39]
	s_cbranch_scc0 .LBB0_741
	s_and_b64 vcc, exec, s[22:23]
	s_cbranch_vccz .LBB0_744
	s_barrier

.LBB0_836:
	ds_read_b128 v[88:91], v235
	ds_read_b128 v[92:95], v235 offset:1024
	ds_read_b128 v[104:107], v235 offset:2048
	ds_read_b128 v[108:111], v235 offset:3072
	ds_read_b128 v[136:139], v236
	ds_read_b128 v[140:143], v236 offset:1024
	ds_read_b128 v[148:151], v236 offset:2048
	ds_read_b128 v[152:155], v236 offset:3072
	s_add_u32 s42, s40, 0xfffc0080
	s_addc_u32 s43, s41, -1
	s_cmp_eq_u32 s63, 12
	s_cselect_b32 s45, s29, s43
	s_cselect_b32 s44, s37, s42
	s_cselect_b32 s43, s27, s62
	s_cselect_b32 s42, s39, s61
	v_lshl_add_u64 v[208:209], s[40:41], 0, v[200:201]
	s_add_i32 m0, s48, 0xc000
	ds_read_b128 v[160:163], v237
	ds_read_b128 v[164:167], v237 offset:1024
	ds_read_b128 v[168:171], v237 offset:2048
	ds_read_b128 v[172:175], v237 offset:3072
	ds_read_b128 v[176:179], v237 offset:4096
	ds_read_b128 v[180:183], v237 offset:5120
	ds_read_b128 v[184:187], v237 offset:6144
	ds_read_b128 v[188:191], v237 offset:7168
	global_load_lds_dwordx4 v[208:209], off
	v_lshl_add_u64 v[208:209], s[40:41], 0, v[202:203]
	s_add_i32 m0, s48, 0xe000
	s_nop 0
	global_load_lds_dwordx4 v[208:209], off
	s_waitcnt vmcnt(8)
	s_waitcnt lgkmcnt(0)
	s_barrier
	s_setprio 1
	s_waitcnt lgkmcnt(0)
	v_mfma_f32_16x16x32_bf16 v[124:127], v[88:91], v[160:163], v[124:127]
	v_mfma_f32_16x16x32_bf16 v[120:123], v[104:107], v[160:163], v[120:123]
	v_mfma_f32_16x16x32_bf16 v[156:159], v[88:91], v[168:171], v[156:159]
	v_mfma_f32_16x16x32_bf16 v[144:147], v[104:107], v[168:171], v[144:147]
	v_mfma_f32_16x16x32_bf16 v[100:103], v[88:91], v[176:179], v[100:103]
	v_mfma_f32_16x16x32_bf16 v[96:99], v[104:107], v[176:179], v[96:99]
	v_mfma_f32_16x16x32_bf16 v[76:79], v[88:91], v[184:187], v[76:79]
	v_mfma_f32_16x16x32_bf16 v[72:75], v[104:107], v[184:187], v[72:75]
	v_mfma_f32_16x16x32_bf16 v[124:127], v[92:95], v[164:167], v[124:127]
	v_mfma_f32_16x16x32_bf16 v[120:123], v[108:111], v[164:167], v[120:123]
	v_mfma_f32_16x16x32_bf16 v[156:159], v[92:95], v[172:175], v[156:159]
	v_mfma_f32_16x16x32_bf16 v[144:147], v[108:111], v[172:175], v[144:147]
	v_mfma_f32_16x16x32_bf16 v[100:103], v[92:95], v[180:183], v[100:103]
	v_mfma_f32_16x16x32_bf16 v[96:99], v[108:111], v[180:183], v[96:99]
	v_mfma_f32_16x16x32_bf16 v[76:79], v[92:95], v[188:191], v[76:79]
	v_mfma_f32_16x16x32_bf16 v[72:75], v[108:111], v[188:191], v[72:75]
	v_mfma_f32_16x16x32_bf16 v[116:119], v[136:139], v[160:163], v[116:119]
	v_mfma_f32_16x16x32_bf16 v[112:115], v[148:151], v[160:163], v[112:115]
	v_mfma_f32_16x16x32_bf16 v[132:135], v[136:139], v[168:171], v[132:135]
	v_mfma_f32_16x16x32_bf16 v[128:131], v[148:151], v[168:171], v[128:131]
	v_mfma_f32_16x16x32_bf16 v[84:87], v[136:139], v[176:179], v[84:87]
	v_mfma_f32_16x16x32_bf16 v[80:83], v[148:151], v[176:179], v[80:83]
	v_mfma_f32_16x16x32_bf16 v[68:71], v[136:139], v[184:187], v[68:71]
	v_mfma_f32_16x16x32_bf16 v[64:67], v[148:151], v[184:187], v[64:67]
	v_mfma_f32_16x16x32_bf16 v[116:119], v[140:143], v[164:167], v[116:119]
	v_mfma_f32_16x16x32_bf16 v[112:115], v[152:155], v[164:167], v[112:115]
	v_mfma_f32_16x16x32_bf16 v[132:135], v[140:143], v[172:175], v[132:135]
	v_mfma_f32_16x16x32_bf16 v[128:131], v[152:155], v[172:175], v[128:131]
	v_mfma_f32_16x16x32_bf16 v[84:87], v[140:143], v[180:183], v[84:87]
	v_mfma_f32_16x16x32_bf16 v[80:83], v[152:155], v[180:183], v[80:83]
	v_mfma_f32_16x16x32_bf16 v[68:71], v[140:143], v[188:191], v[68:71]
	v_mfma_f32_16x16x32_bf16 v[64:67], v[152:155], v[188:191], v[64:67]
	s_setprio 0
	s_barrier
	s_add_i32 s64, s59, s47
	v_lshl_add_u64 v[208:209], s[42:43], 0, v[194:195]
	s_mov_b32 m0, s64
	ds_read_b128 v[160:163], v237 offset:16384
	ds_read_b128 v[164:167], v237 offset:17408
	ds_read_b128 v[168:171], v237 offset:18432
	ds_read_b128 v[172:175], v237 offset:19456
	ds_read_b128 v[176:179], v237 offset:20480
	ds_read_b128 v[180:183], v237 offset:21504
	ds_read_b128 v[184:187], v237 offset:22528
	ds_read_b128 v[188:191], v237 offset:23552
	global_load_lds_dwordx4 v[208:209], off
	s_add_i32 m0, s64, 0x2000
	s_add_u32 s64, s42, 0x40000
	v_lshl_add_u64 v[210:211], s[42:43], 0, v[198:199]
	s_addc_u32 s65, s43, 0
	s_add_i32 s66, s60, s47
	global_load_lds_dwordx4 v[210:211], off
	v_lshl_add_u64 v[212:213], s[64:65], 0, v[194:195]
	s_mov_b32 m0, s66
	v_lshl_add_u64 v[214:215], s[44:45], 0, v[196:197]
	global_load_lds_dwordx4 v[212:213], off
	v_lshl_add_u64 v[212:213], s[64:65], 0, v[198:199]
	s_add_i32 m0, s66, 0x2000
	s_nop 0
	global_load_lds_dwordx4 v[212:213], off
	v_lshl_add_u64 v[212:213], s[44:45], 0, v[192:193]
	s_mov_b32 m0, s48
	s_nop 0
	global_load_lds_dwordx4 v[212:213], off
	s_mov_b32 m0, s49
	s_nop 0
	global_load_lds_dwordx4 v[214:215], off
	s_waitcnt vmcnt(8)
	s_waitcnt lgkmcnt(0)
	s_barrier
	s_setprio 1
	s_waitcnt lgkmcnt(0)
	v_mfma_f32_16x16x32_bf16 v[60:63], v[88:91], v[160:163], v[60:63]
	v_mfma_f32_16x16x32_bf16 v[56:59], v[104:107], v[160:163], v[56:59]
	v_mfma_f32_16x16x32_bf16 v[44:47], v[88:91], v[168:171], v[44:47]
	v_mfma_f32_16x16x32_bf16 v[40:43], v[104:107], v[168:171], v[40:43]
	v_mfma_f32_16x16x32_bf16 v[28:31], v[88:91], v[176:179], v[28:31]
	v_mfma_f32_16x16x32_bf16 v[24:27], v[104:107], v[176:179], v[24:27]
	v_mfma_f32_16x16x32_bf16 v[12:15], v[88:91], v[184:187], v[12:15]
	v_mfma_f32_16x16x32_bf16 v[8:11], v[104:107], v[184:187], v[8:11]
	v_mfma_f32_16x16x32_bf16 v[60:63], v[92:95], v[164:167], v[60:63]
	v_mfma_f32_16x16x32_bf16 v[56:59], v[108:111], v[164:167], v[56:59]
	v_mfma_f32_16x16x32_bf16 v[44:47], v[92:95], v[172:175], v[44:47]
	v_mfma_f32_16x16x32_bf16 v[40:43], v[108:111], v[172:175], v[40:43]
	v_mfma_f32_16x16x32_bf16 v[28:31], v[92:95], v[180:183], v[28:31]
	v_mfma_f32_16x16x32_bf16 v[24:27], v[108:111], v[180:183], v[24:27]
	v_mfma_f32_16x16x32_bf16 v[12:15], v[92:95], v[188:191], v[12:15]
	v_mfma_f32_16x16x32_bf16 v[8:11], v[108:111], v[188:191], v[8:11]
	v_mfma_f32_16x16x32_bf16 v[52:55], v[136:139], v[160:163], v[52:55]
	v_mfma_f32_16x16x32_bf16 v[48:51], v[148:151], v[160:163], v[48:51]
	v_mfma_f32_16x16x32_bf16 v[36:39], v[136:139], v[168:171], v[36:39]
	v_mfma_f32_16x16x32_bf16 v[32:35], v[148:151], v[168:171], v[32:35]
	v_mfma_f32_16x16x32_bf16 v[20:23], v[136:139], v[176:179], v[20:23]
	v_mfma_f32_16x16x32_bf16 v[16:19], v[148:151], v[176:179], v[16:19]
	v_mfma_f32_16x16x32_bf16 v[4:7], v[136:139], v[184:187], v[4:7]
	v_mfma_f32_16x16x32_bf16 v[0:3], v[148:151], v[184:187], v[0:3]
	v_mfma_f32_16x16x32_bf16 v[52:55], v[140:143], v[164:167], v[52:55]
	v_mfma_f32_16x16x32_bf16 v[48:51], v[152:155], v[164:167], v[48:51]
	v_mfma_f32_16x16x32_bf16 v[36:39], v[140:143], v[172:175], v[36:39]
	v_mfma_f32_16x16x32_bf16 v[32:35], v[152:155], v[172:175], v[32:35]
	v_mfma_f32_16x16x32_bf16 v[20:23], v[140:143], v[180:183], v[20:23]
	v_mfma_f32_16x16x32_bf16 v[16:19], v[152:155], v[180:183], v[16:19]
	v_mfma_f32_16x16x32_bf16 v[4:7], v[140:143], v[188:191], v[4:7]
	v_mfma_f32_16x16x32_bf16 v[0:3], v[152:155], v[188:191], v[0:3]
	s_setprio 0
	s_barrier
	s_add_i32 s64, 0, 0x18000
	s_add_i32 s65, 0, 0x1c000
	v_add_u32_e32 v108, s64, v233
	v_add_u32_e32 v152, s65, v233
	ds_read_b128 v[88:91], v108
	ds_read_b128 v[92:95], v108 offset:1024
	ds_read_b128 v[104:107], v108 offset:2048
	ds_read_b128 v[108:111], v108 offset:3072
	ds_read_b128 v[136:139], v152
	ds_read_b128 v[140:143], v152 offset:1024
	ds_read_b128 v[148:151], v152 offset:2048
	ds_read_b128 v[152:155], v152 offset:3072
	s_add_u32 s44, s44, 0x40000
	s_addc_u32 s45, s45, 0
	s_mov_b32 m0, s50
	v_lshl_add_u64 v[216:217], s[44:45], 0, v[192:193]
	ds_read_b128 v[160:163], v237 offset:32768
	ds_read_b128 v[164:167], v237 offset:33792
	ds_read_b128 v[168:171], v237 offset:34816
	ds_read_b128 v[172:175], v237 offset:35840
	ds_read_b128 v[176:179], v237 offset:36864
	ds_read_b128 v[180:183], v237 offset:37888
	ds_read_b128 v[184:187], v237 offset:38912
	ds_read_b128 v[188:191], v237 offset:39936
	global_load_lds_dwordx4 v[216:217], off
	v_lshl_add_u64 v[216:217], s[44:45], 0, v[196:197]
	s_mov_b32 m0, s51
	s_nop 0
	global_load_lds_dwordx4 v[216:217], off
	s_waitcnt vmcnt(8)
	s_waitcnt lgkmcnt(0)
	s_barrier
	s_setprio 1
	s_waitcnt lgkmcnt(0)
	v_mfma_f32_16x16x32_bf16 v[124:127], v[88:91], v[160:163], v[124:127]
	v_mfma_f32_16x16x32_bf16 v[120:123], v[104:107], v[160:163], v[120:123]
	v_mfma_f32_16x16x32_bf16 v[156:159], v[88:91], v[168:171], v[156:159]
	v_mfma_f32_16x16x32_bf16 v[144:147], v[104:107], v[168:171], v[144:147]
	v_mfma_f32_16x16x32_bf16 v[100:103], v[88:91], v[176:179], v[100:103]
	v_mfma_f32_16x16x32_bf16 v[96:99], v[104:107], v[176:179], v[96:99]
	v_mfma_f32_16x16x32_bf16 v[76:79], v[88:91], v[184:187], v[76:79]
	v_mfma_f32_16x16x32_bf16 v[72:75], v[104:107], v[184:187], v[72:75]
	v_mfma_f32_16x16x32_bf16 v[124:127], v[92:95], v[164:167], v[124:127]
	v_mfma_f32_16x16x32_bf16 v[120:123], v[108:111], v[164:167], v[120:123]
	v_mfma_f32_16x16x32_bf16 v[156:159], v[92:95], v[172:175], v[156:159]
	v_mfma_f32_16x16x32_bf16 v[144:147], v[108:111], v[172:175], v[144:147]
	v_mfma_f32_16x16x32_bf16 v[100:103], v[92:95], v[180:183], v[100:103]
	v_mfma_f32_16x16x32_bf16 v[96:99], v[108:111], v[180:183], v[96:99]
	v_mfma_f32_16x16x32_bf16 v[76:79], v[92:95], v[188:191], v[76:79]
	v_mfma_f32_16x16x32_bf16 v[72:75], v[108:111], v[188:191], v[72:75]
	v_mfma_f32_16x16x32_bf16 v[116:119], v[136:139], v[160:163], v[116:119]
	v_mfma_f32_16x16x32_bf16 v[112:115], v[148:151], v[160:163], v[112:115]
	v_mfma_f32_16x16x32_bf16 v[132:135], v[136:139], v[168:171], v[132:135]
	v_mfma_f32_16x16x32_bf16 v[128:131], v[148:151], v[168:171], v[128:131]
	v_mfma_f32_16x16x32_bf16 v[84:87], v[136:139], v[176:179], v[84:87]
	v_mfma_f32_16x16x32_bf16 v[80:83], v[148:151], v[176:179], v[80:83]
	v_mfma_f32_16x16x32_bf16 v[68:71], v[136:139], v[184:187], v[68:71]
	v_mfma_f32_16x16x32_bf16 v[64:67], v[148:151], v[184:187], v[64:67]
	v_mfma_f32_16x16x32_bf16 v[116:119], v[140:143], v[164:167], v[116:119]
	v_mfma_f32_16x16x32_bf16 v[112:115], v[152:155], v[164:167], v[112:115]
	v_mfma_f32_16x16x32_bf16 v[132:135], v[140:143], v[172:175], v[132:135]
	v_mfma_f32_16x16x32_bf16 v[128:131], v[152:155], v[172:175], v[128:131]
	v_mfma_f32_16x16x32_bf16 v[84:87], v[140:143], v[180:183], v[84:87]
	v_mfma_f32_16x16x32_bf16 v[80:83], v[152:155], v[180:183], v[80:83]
	v_mfma_f32_16x16x32_bf16 v[68:71], v[140:143], v[188:191], v[68:71]
	v_mfma_f32_16x16x32_bf16 v[64:67], v[152:155], v[188:191], v[64:67]
	s_setprio 0
	s_barrier
	s_add_i32 s44, s64, s47
	v_lshl_add_u64 v[208:209], v[208:209], 0, s[22:23]
	s_mov_b32 m0, s44
	ds_read_b128 v[160:163], v237 offset:49152
	ds_read_b128 v[164:167], v237 offset:50176
	ds_read_b128 v[168:171], v237 offset:51200
	ds_read_b128 v[172:175], v237 offset:52224
	ds_read_b128 v[176:179], v237 offset:53248
	ds_read_b128 v[180:183], v237 offset:54272
	ds_read_b128 v[184:187], v237 offset:55296
	ds_read_b128 v[188:191], v237 offset:56320
	global_load_lds_dwordx4 v[208:209], off
	s_add_i32 m0, s44, 0x2000
	s_add_u32 s42, s42, 0x40080
	v_lshl_add_u64 v[208:209], v[210:211], 0, s[22:23]
	s_addc_u32 s43, s43, 0
	s_add_i32 s44, s65, s47
	global_load_lds_dwordx4 v[208:209], off
	v_lshl_add_u64 v[208:209], s[42:43], 0, v[194:195]
	s_mov_b32 m0, s44
	s_nop 0
	global_load_lds_dwordx4 v[208:209], off
	v_lshl_add_u64 v[208:209], s[42:43], 0, v[198:199]
	s_add_i32 m0, s44, 0x2000
	s_nop 0
	global_load_lds_dwordx4 v[208:209], off
	v_lshl_add_u64 v[208:209], v[212:213], 0, s[22:23]
	s_mov_b32 m0, s55
	s_nop 0
	global_load_lds_dwordx4 v[208:209], off
	v_lshl_add_u64 v[208:209], v[214:215], 0, s[22:23]
	s_mov_b32 m0, s56
	s_nop 0
	global_load_lds_dwordx4 v[208:209], off
	s_waitcnt vmcnt(8)
	s_waitcnt lgkmcnt(0)
	s_barrier
	s_setprio 1
	s_waitcnt lgkmcnt(0)
	v_mfma_f32_16x16x32_bf16 v[60:63], v[88:91], v[160:163], v[60:63]
	v_mfma_f32_16x16x32_bf16 v[56:59], v[104:107], v[160:163], v[56:59]
	v_mfma_f32_16x16x32_bf16 v[44:47], v[88:91], v[168:171], v[44:47]
	v_mfma_f32_16x16x32_bf16 v[40:43], v[104:107], v[168:171], v[40:43]
	v_mfma_f32_16x16x32_bf16 v[28:31], v[88:91], v[176:179], v[28:31]
	v_mfma_f32_16x16x32_bf16 v[24:27], v[104:107], v[176:179], v[24:27]
	v_mfma_f32_16x16x32_bf16 v[12:15], v[88:91], v[184:187], v[12:15]
	v_mfma_f32_16x16x32_bf16 v[8:11], v[104:107], v[184:187], v[8:11]
	v_mfma_f32_16x16x32_bf16 v[60:63], v[92:95], v[164:167], v[60:63]
	v_mfma_f32_16x16x32_bf16 v[56:59], v[108:111], v[164:167], v[56:59]
	v_mfma_f32_16x16x32_bf16 v[44:47], v[92:95], v[172:175], v[44:47]
	v_mfma_f32_16x16x32_bf16 v[40:43], v[108:111], v[172:175], v[40:43]
	v_mfma_f32_16x16x32_bf16 v[28:31], v[92:95], v[180:183], v[28:31]
	v_mfma_f32_16x16x32_bf16 v[24:27], v[108:111], v[180:183], v[24:27]
	v_mfma_f32_16x16x32_bf16 v[12:15], v[92:95], v[188:191], v[12:15]
	v_mfma_f32_16x16x32_bf16 v[8:11], v[108:111], v[188:191], v[8:11]
	v_mfma_f32_16x16x32_bf16 v[52:55], v[136:139], v[160:163], v[52:55]
	v_mfma_f32_16x16x32_bf16 v[48:51], v[148:151], v[160:163], v[48:51]
	v_mfma_f32_16x16x32_bf16 v[36:39], v[136:139], v[168:171], v[36:39]
	v_mfma_f32_16x16x32_bf16 v[32:35], v[148:151], v[168:171], v[32:35]
	v_mfma_f32_16x16x32_bf16 v[20:23], v[136:139], v[176:179], v[20:23]
	v_mfma_f32_16x16x32_bf16 v[16:19], v[148:151], v[176:179], v[16:19]
	v_mfma_f32_16x16x32_bf16 v[4:7], v[136:139], v[184:187], v[4:7]
	v_mfma_f32_16x16x32_bf16 v[0:3], v[148:151], v[184:187], v[0:3]
	v_mfma_f32_16x16x32_bf16 v[52:55], v[140:143], v[164:167], v[52:55]
	v_mfma_f32_16x16x32_bf16 v[48:51], v[152:155], v[164:167], v[48:51]
	v_mfma_f32_16x16x32_bf16 v[36:39], v[140:143], v[172:175], v[36:39]
	v_mfma_f32_16x16x32_bf16 v[32:35], v[152:155], v[172:175], v[32:35]
	v_mfma_f32_16x16x32_bf16 v[20:23], v[140:143], v[180:183], v[20:23]
	v_mfma_f32_16x16x32_bf16 v[16:19], v[152:155], v[180:183], v[16:19]
	v_mfma_f32_16x16x32_bf16 v[4:7], v[140:143], v[188:191], v[4:7]
	v_mfma_f32_16x16x32_bf16 v[0:3], v[152:155], v[188:191], v[0:3]
	s_setprio 0
	s_barrier
	s_add_i32 s63, s63, 2
	s_add_u32 s40, s40, 0x100
	s_addc_u32 s41, s41, 0
	s_add_u32 s61, s61, 0x100
	s_addc_u32 s62, s62, 0
	s_cmp_gt_u32 s63, 13
	s_cbranch_scc0 .LBB0_836
	s_and_b64 vcc, exec, s[24:25]
	s_cbranch_vccz .LBB0_839
	s_barrier

.LBB0_862:
	global_load_dword v240, v[182:183], off sc1
	global_load_dword v242, v[182:183], off offset:64 sc1
	global_load_dword v244, v[182:183], off offset:128 sc1
	global_load_dword v246, v[182:183], off offset:192 sc1
	global_load_dword v248, v[182:183], off offset:512 sc1
	global_load_dword v250, v[182:183], off offset:576 sc1
	global_load_dword v252, v[182:183], off offset:640 sc1
	global_load_dword v164, v[182:183], off offset:704 sc1
	s_andn2_b64 vcc, exec, s[4:5]
	s_mov_b64 s[4:5], -1
	v_lshlrev_b64 v[70:71], 12, v[216:217]
	v_lshlrev_b64 v[68:69], 2, v[218:219]
	v_lshl_add_u64 v[70:71], s[10:11], 0, v[70:71]
	v_lshl_add_u64 v[70:71], v[70:71], 0, v[68:69]
	v_mbcnt_lo_u32_b32 v101, -1, 0
	v_mbcnt_hi_u32_b32 v101, -1, v101
	v_readfirstlane_b32 s82, v70
	v_readfirstlane_b32 s83, v71
	s_lshl_b32 s86, s47, 1
	s_add_i32 s86, s86, 0x20000
	v_and_b32_e32 v102, 15, v101
	v_lshrrev_b32_e32 v103, 4, v101
	v_lshlrev_b32_e32 v103, 1, v103
	v_and_b32_e32 v96, 7, v102
	v_xor_b32_e32 v96, v96, v103
	v_xor_b32_e32 v97, 1, v96
	v_lshlrev_b32_e32 v96, 4, v96
	v_lshlrev_b32_e32 v97, 4, v97
	v_lshl_add_u32 v96, v102, 7, v96
	v_lshl_add_u32 v97, v102, 7, v97
	v_add_u32_e32 v96, s86, v96
	v_add_u32_e32 v97, s86, v97
	v_lshrrev_b32_e32 v102, 3, v101
	v_and_b32_e32 v103, 7, v101
	v_xor_b32_e32 v98, v103, v102
	v_lshlrev_b32_e32 v98, 4, v98
	v_lshl_add_u32 v98, v102, 7, v98
	v_add_u32_e32 v98, s86, v98
	v_lshlrev_b32_e32 v99, 4, v103
	v_lshl_add_u32 v99, v102, 12, v99
	v_add_u32_e32 v100, 0x8000, v99
	s_waitcnt vmcnt(0)
	v_fmamk_f32 v240, v240, 0x3a800000, v239
	v_fmamk_f32 v242, v242, 0x3a800000, v239
	v_fmamk_f32 v244, v244, 0x3a800000, v239
	v_fmamk_f32 v246, v246, 0x3a800000, v239
	v_fmamk_f32 v248, v248, 0x3a800000, v239
	v_fmamk_f32 v250, v250, 0x3a800000, v239
	v_fmamk_f32 v252, v252, 0x3a800000, v239
	v_fmamk_f32 v164, v164, 0x3a800000, v239
	v_rsq_f32_e32 v240, v240
	v_rsq_f32_e32 v242, v242
	v_rsq_f32_e32 v244, v244
	v_rsq_f32_e32 v246, v246
	v_rsq_f32_e32 v248, v248
	v_rsq_f32_e32 v250, v250
	v_rsq_f32_e32 v252, v252
	v_rsq_f32_e32 v164, v164
	s_nop 0
	v_pk_mul_f32 v[68:69], v[220:221], v[240:241] op_sel_hi:[1,0]
	v_pk_mul_f32 v[70:71], v[184:185], v[240:241] op_sel_hi:[1,0]
	v_pk_mul_f32 v[112:113], v[12:13], v[68:69]
	v_pk_mul_f32 v[114:115], v[14:15], v[70:71]
	v_pk_mul_f32 v[156:157], v[222:223], v[240:241] op_sel_hi:[1,0]
	v_pk_mul_f32 v[158:159], v[186:187], v[240:241] op_sel_hi:[1,0]
	v_pk_mul_f32 v[116:117], v[4:5], v[156:157]
	v_pk_mul_f32 v[118:119], v[6:7], v[158:159]
	ds_write_b128 v96, v[112:115]
	ds_write_b128 v97, v[116:119]
	ds_read_b128 v[128:131], v98
	ds_read_b128 v[132:135], v98 offset:1024
	v_pk_mul_f32 v[68:69], v[188:189], v[240:241] op_sel_hi:[1,0]
	v_pk_mul_f32 v[70:71], v[176:177], v[240:241] op_sel_hi:[1,0]
	v_pk_mul_f32 v[120:121], v[8:9], v[68:69]
	v_pk_mul_f32 v[122:123], v[10:11], v[70:71]
	v_pk_mul_f32 v[156:157], v[190:191], v[240:241] op_sel_hi:[1,0]
	v_pk_mul_f32 v[158:159], v[178:179], v[240:241] op_sel_hi:[1,0]
	v_pk_mul_f32 v[124:125], v[0:1], v[156:157]
	v_pk_mul_f32 v[126:127], v[2:3], v[158:159]
	s_waitcnt lgkmcnt(0)
	s_mov_b32 s84, s82
	s_mov_b32 s85, s83
	global_store_dwordx4 v99, v[128:131], s[84:85]
	global_store_dwordx4 v100, v[132:135], s[84:85]
	ds_write_b128 v96, v[120:123]
	ds_write_b128 v97, v[124:127]
	ds_read_b128 v[84:87], v98
	ds_read_b128 v[92:95], v98 offset:1024
	v_pk_mul_f32 v[68:69], v[224:225], v[242:243] op_sel_hi:[1,0]
	v_pk_mul_f32 v[70:71], v[168:169], v[242:243] op_sel_hi:[1,0]
	v_pk_mul_f32 v[112:113], v[12:13], v[68:69]
	v_pk_mul_f32 v[114:115], v[14:15], v[70:71]
	v_pk_mul_f32 v[156:157], v[226:227], v[242:243] op_sel_hi:[1,0]
	v_pk_mul_f32 v[158:159], v[170:171], v[242:243] op_sel_hi:[1,0]
	v_pk_mul_f32 v[116:117], v[4:5], v[156:157]
	v_pk_mul_f32 v[118:119], v[6:7], v[158:159]
	s_waitcnt lgkmcnt(0)
	global_store_dwordx4 v99, v[84:87], s[84:85] offset:512
	global_store_dwordx4 v100, v[92:95], s[84:85] offset:512
	ds_write_b128 v96, v[112:115]
	ds_write_b128 v97, v[116:119]
	ds_read_b128 v[128:131], v98
	ds_read_b128 v[132:135], v98 offset:1024
	v_pk_mul_f32 v[68:69], v[172:173], v[242:243] op_sel_hi:[1,0]
	v_pk_mul_f32 v[70:71], v[160:161], v[242:243] op_sel_hi:[1,0]
	v_pk_mul_f32 v[120:121], v[8:9], v[68:69]
	v_pk_mul_f32 v[122:123], v[10:11], v[70:71]
	v_pk_mul_f32 v[156:157], v[174:175], v[242:243] op_sel_hi:[1,0]
	v_pk_mul_f32 v[158:159], v[162:163], v[242:243] op_sel_hi:[1,0]
	v_pk_mul_f32 v[124:125], v[0:1], v[156:157]
	v_pk_mul_f32 v[126:127], v[2:3], v[158:159]
	s_waitcnt lgkmcnt(0)
	s_add_u32 s84, s82, 0x10000
	s_addc_u32 s85, s83, 0
	global_store_dwordx4 v99, v[128:131], s[84:85]
	global_store_dwordx4 v100, v[132:135], s[84:85]
	ds_write_b128 v96, v[120:123]
	ds_write_b128 v97, v[124:127]
	ds_read_b128 v[84:87], v98
	ds_read_b128 v[92:95], v98 offset:1024
	v_pk_mul_f32 v[68:69], v[166:167], v[244:245] op_sel_hi:[1,0]
	v_pk_mul_f32 v[70:71], v[148:149], v[244:245] op_sel_hi:[1,0]
	v_pk_mul_f32 v[112:113], v[12:13], v[68:69]
	v_pk_mul_f32 v[114:115], v[14:15], v[70:71]
	v_pk_mul_f32 v[156:157], v[228:229], v[244:245] op_sel_hi:[1,0]
	v_pk_mul_f32 v[158:159], v[150:151], v[244:245] op_sel_hi:[1,0]
	v_pk_mul_f32 v[116:117], v[4:5], v[156:157]
	v_pk_mul_f32 v[118:119], v[6:7], v[158:159]
	s_waitcnt lgkmcnt(0)
	global_store_dwordx4 v99, v[84:87], s[84:85] offset:512
	global_store_dwordx4 v100, v[92:95], s[84:85] offset:512
	ds_write_b128 v96, v[112:115]
	ds_write_b128 v97, v[116:119]
	ds_read_b128 v[128:131], v98
	ds_read_b128 v[132:135], v98 offset:1024
	v_pk_mul_f32 v[68:69], v[152:153], v[244:245] op_sel_hi:[1,0]
	v_pk_mul_f32 v[70:71], v[136:137], v[244:245] op_sel_hi:[1,0]
	v_pk_mul_f32 v[120:121], v[8:9], v[68:69]
	v_pk_mul_f32 v[122:123], v[10:11], v[70:71]
	v_pk_mul_f32 v[156:157], v[154:155], v[244:245] op_sel_hi:[1,0]
	v_pk_mul_f32 v[158:159], v[138:139], v[244:245] op_sel_hi:[1,0]
	v_pk_mul_f32 v[124:125], v[0:1], v[156:157]
	v_pk_mul_f32 v[126:127], v[2:3], v[158:159]
	s_waitcnt lgkmcnt(0)
	s_add_u32 s84, s82, 0x20000
	s_addc_u32 s85, s83, 0
	global_store_dwordx4 v99, v[128:131], s[84:85]
	global_store_dwordx4 v100, v[132:135], s[84:85]
	ds_write_b128 v96, v[120:123]
	ds_write_b128 v97, v[124:127]
	ds_read_b128 v[84:87], v98
	ds_read_b128 v[92:95], v98 offset:1024
	v_pk_mul_f32 v[68:69], v[142:143], v[246:247] op_sel_hi:[1,0]
	v_pk_mul_f32 v[70:71], v[104:105], v[246:247] op_sel_hi:[1,0]
	v_pk_mul_f32 v[112:113], v[12:13], v[68:69]
	v_pk_mul_f32 v[114:115], v[14:15], v[70:71]
	v_pk_mul_f32 v[156:157], v[230:231], v[246:247] op_sel_hi:[1,0]
	v_pk_mul_f32 v[158:159], v[106:107], v[246:247] op_sel_hi:[1,0]
	v_pk_mul_f32 v[116:117], v[4:5], v[156:157]
	v_pk_mul_f32 v[118:119], v[6:7], v[158:159]
	s_waitcnt lgkmcnt(0)
	global_store_dwordx4 v99, v[84:87], s[84:85] offset:512
	global_store_dwordx4 v100, v[92:95], s[84:85] offset:512
	ds_write_b128 v96, v[112:115]
	ds_write_b128 v97, v[116:119]
	ds_read_b128 v[128:131], v98
	ds_read_b128 v[132:135], v98 offset:1024
	v_pk_mul_f32 v[68:69], v[108:109], v[246:247] op_sel_hi:[1,0]
	v_pk_mul_f32 v[70:71], v[88:89], v[246:247] op_sel_hi:[1,0]
	v_pk_mul_f32 v[120:121], v[8:9], v[68:69]
	v_pk_mul_f32 v[122:123], v[10:11], v[70:71]
	v_pk_mul_f32 v[156:157], v[110:111], v[246:247] op_sel_hi:[1,0]
	v_pk_mul_f32 v[158:159], v[90:91], v[246:247] op_sel_hi:[1,0]
	v_pk_mul_f32 v[124:125], v[0:1], v[156:157]
	v_pk_mul_f32 v[126:127], v[2:3], v[158:159]
	s_waitcnt lgkmcnt(0)
	s_add_u32 s84, s82, 0x30000
	s_addc_u32 s85, s83, 0
	global_store_dwordx4 v99, v[128:131], s[84:85]
	global_store_dwordx4 v100, v[132:135], s[84:85]
	ds_write_b128 v96, v[120:123]
	ds_write_b128 v97, v[124:127]
	ds_read_b128 v[84:87], v98
	ds_read_b128 v[92:95], v98 offset:1024
	v_pk_mul_f32 v[68:69], v[56:57], v[248:249] op_sel_hi:[1,0]
	v_pk_mul_f32 v[70:71], v[58:59], v[248:249] op_sel_hi:[1,0]
	v_pk_mul_f32 v[112:113], v[12:13], v[68:69]
	v_pk_mul_f32 v[114:115], v[14:15], v[70:71]
	v_pk_mul_f32 v[156:157], v[60:61], v[248:249] op_sel_hi:[1,0]
	v_pk_mul_f32 v[158:159], v[62:63], v[248:249] op_sel_hi:[1,0]
	v_pk_mul_f32 v[116:117], v[4:5], v[156:157]
	v_pk_mul_f32 v[118:119], v[6:7], v[158:159]
	s_waitcnt lgkmcnt(0)
	global_store_dwordx4 v99, v[84:87], s[84:85] offset:512
	global_store_dwordx4 v100, v[92:95], s[84:85] offset:512
	ds_write_b128 v96, v[112:115]
	ds_write_b128 v97, v[116:119]
	ds_read_b128 v[128:131], v98
	ds_read_b128 v[132:135], v98 offset:1024
	v_pk_mul_f32 v[68:69], v[48:49], v[248:249] op_sel_hi:[1,0]
	v_pk_mul_f32 v[70:71], v[50:51], v[248:249] op_sel_hi:[1,0]
	v_pk_mul_f32 v[120:121], v[8:9], v[68:69]
	v_pk_mul_f32 v[122:123], v[10:11], v[70:71]
	v_pk_mul_f32 v[156:157], v[52:53], v[248:249] op_sel_hi:[1,0]
	v_pk_mul_f32 v[158:159], v[54:55], v[248:249] op_sel_hi:[1,0]
	v_pk_mul_f32 v[124:125], v[0:1], v[156:157]
	v_pk_mul_f32 v[126:127], v[2:3], v[158:159]
	s_waitcnt lgkmcnt(0)
	s_add_u32 s84, s82, 0x80000
	s_addc_u32 s85, s83, 0
	global_store_dwordx4 v99, v[128:131], s[84:85]
	global_store_dwordx4 v100, v[132:135], s[84:85]
	ds_write_b128 v96, v[120:123]
	ds_write_b128 v97, v[124:127]
	ds_read_b128 v[84:87], v98
	ds_read_b128 v[92:95], v98 offset:1024
	v_pk_mul_f32 v[68:69], v[40:41], v[250:251] op_sel_hi:[1,0]
	v_pk_mul_f32 v[70:71], v[42:43], v[250:251] op_sel_hi:[1,0]
	v_pk_mul_f32 v[112:113], v[12:13], v[68:69]
	v_pk_mul_f32 v[114:115], v[14:15], v[70:71]
	v_pk_mul_f32 v[156:157], v[44:45], v[250:251] op_sel_hi:[1,0]
	v_pk_mul_f32 v[158:159], v[46:47], v[250:251] op_sel_hi:[1,0]
	v_pk_mul_f32 v[116:117], v[4:5], v[156:157]
	v_pk_mul_f32 v[118:119], v[6:7], v[158:159]
	s_waitcnt lgkmcnt(0)
	global_store_dwordx4 v99, v[84:87], s[84:85] offset:512
	global_store_dwordx4 v100, v[92:95], s[84:85] offset:512
	ds_write_b128 v96, v[112:115]
	ds_write_b128 v97, v[116:119]
	ds_read_b128 v[128:131], v98
	ds_read_b128 v[132:135], v98 offset:1024
	v_pk_mul_f32 v[68:69], v[32:33], v[250:251] op_sel_hi:[1,0]
	v_pk_mul_f32 v[70:71], v[34:35], v[250:251] op_sel_hi:[1,0]
	v_pk_mul_f32 v[120:121], v[8:9], v[68:69]
	v_pk_mul_f32 v[122:123], v[10:11], v[70:71]
	v_pk_mul_f32 v[156:157], v[36:37], v[250:251] op_sel_hi:[1,0]
	v_pk_mul_f32 v[158:159], v[38:39], v[250:251] op_sel_hi:[1,0]
	v_pk_mul_f32 v[124:125], v[0:1], v[156:157]
	v_pk_mul_f32 v[126:127], v[2:3], v[158:159]
	s_waitcnt lgkmcnt(0)
	s_add_u32 s84, s82, 0x90000
	s_addc_u32 s85, s83, 0
	global_store_dwordx4 v99, v[128:131], s[84:85]
	global_store_dwordx4 v100, v[132:135], s[84:85]
	ds_write_b128 v96, v[120:123]
	ds_write_b128 v97, v[124:127]
	ds_read_b128 v[84:87], v98
	ds_read_b128 v[92:95], v98 offset:1024
	v_pk_mul_f32 v[68:69], v[24:25], v[252:253] op_sel_hi:[1,0]
	v_pk_mul_f32 v[70:71], v[26:27], v[252:253] op_sel_hi:[1,0]
	v_pk_mul_f32 v[112:113], v[12:13], v[68:69]
	v_pk_mul_f32 v[114:115], v[14:15], v[70:71]
	v_pk_mul_f32 v[156:157], v[28:29], v[252:253] op_sel_hi:[1,0]
	v_pk_mul_f32 v[158:159], v[30:31], v[252:253] op_sel_hi:[1,0]
	v_pk_mul_f32 v[116:117], v[4:5], v[156:157]
	v_pk_mul_f32 v[118:119], v[6:7], v[158:159]
	s_waitcnt lgkmcnt(0)
	global_store_dwordx4 v99, v[84:87], s[84:85] offset:512
	global_store_dwordx4 v100, v[92:95], s[84:85] offset:512
	ds_write_b128 v96, v[112:115]
	ds_write_b128 v97, v[116:119]
	ds_read_b128 v[128:131], v98
	ds_read_b128 v[132:135], v98 offset:1024
	v_pk_mul_f32 v[68:69], v[16:17], v[252:253] op_sel_hi:[1,0]
	v_pk_mul_f32 v[70:71], v[18:19], v[252:253] op_sel_hi:[1,0]
	v_pk_mul_f32 v[120:121], v[8:9], v[68:69]
	v_pk_mul_f32 v[122:123], v[10:11], v[70:71]
	v_pk_mul_f32 v[156:157], v[20:21], v[252:253] op_sel_hi:[1,0]
	v_pk_mul_f32 v[158:159], v[22:23], v[252:253] op_sel_hi:[1,0]
	v_pk_mul_f32 v[124:125], v[0:1], v[156:157]
	v_pk_mul_f32 v[126:127], v[2:3], v[158:159]
	s_waitcnt lgkmcnt(0)
	s_add_u32 s84, s82, 0xa0000
	s_addc_u32 s85, s83, 0
	global_store_dwordx4 v99, v[128:131], s[84:85]
	global_store_dwordx4 v100, v[132:135], s[84:85]
	ds_write_b128 v96, v[120:123]
	ds_write_b128 v97, v[124:127]
	ds_read_b128 v[84:87], v98
	ds_read_b128 v[92:95], v98 offset:1024
	v_pk_mul_f32 v[68:69], v[80:81], v[164:165] op_sel_hi:[1,0]
	v_pk_mul_f32 v[70:71], v[72:73], v[164:165] op_sel_hi:[1,0]
	v_pk_mul_f32 v[112:113], v[12:13], v[68:69]
	v_pk_mul_f32 v[114:115], v[14:15], v[70:71]
	v_pk_mul_f32 v[156:157], v[82:83], v[164:165] op_sel_hi:[1,0]
	v_pk_mul_f32 v[158:159], v[74:75], v[164:165] op_sel_hi:[1,0]
	v_pk_mul_f32 v[116:117], v[4:5], v[156:157]
	v_pk_mul_f32 v[118:119], v[6:7], v[158:159]
	s_waitcnt lgkmcnt(0)
	global_store_dwordx4 v99, v[84:87], s[84:85] offset:512
	global_store_dwordx4 v100, v[92:95], s[84:85] offset:512
	ds_write_b128 v96, v[112:115]
	ds_write_b128 v97, v[116:119]
	ds_read_b128 v[128:131], v98
	ds_read_b128 v[132:135], v98 offset:1024
	v_pk_mul_f32 v[68:69], v[76:77], v[164:165] op_sel_hi:[1,0]
	v_pk_mul_f32 v[70:71], v[64:65], v[164:165] op_sel_hi:[1,0]
	v_pk_mul_f32 v[120:121], v[8:9], v[68:69]
	v_pk_mul_f32 v[122:123], v[10:11], v[70:71]
	v_pk_mul_f32 v[156:157], v[78:79], v[164:165] op_sel_hi:[1,0]
	v_pk_mul_f32 v[158:159], v[66:67], v[164:165] op_sel_hi:[1,0]
	v_pk_mul_f32 v[124:125], v[0:1], v[156:157]
	v_pk_mul_f32 v[126:127], v[2:3], v[158:159]
	s_waitcnt lgkmcnt(0)
	s_add_u32 s84, s82, 0xb0000
	s_addc_u32 s85, s83, 0
	global_store_dwordx4 v99, v[128:131], s[84:85]
	global_store_dwordx4 v100, v[132:135], s[84:85]
	ds_write_b128 v96, v[120:123]
	ds_write_b128 v97, v[124:127]
	ds_read_b128 v[84:87], v98
	ds_read_b128 v[92:95], v98 offset:1024
	s_waitcnt lgkmcnt(0)
	global_store_dwordx4 v99, v[84:87], s[84:85] offset:512
	global_store_dwordx4 v100, v[92:95], s[84:85] offset:512
	s_cbranch_vccnz .LBB0_828
	s_andn2_b64 vcc, exec, s[14:15]
	s_cbranch_vccnz .LBB0_827
	s_barrier
	s_branch .LBB0_827
